# no s_setprio flips inside the three load-bound 160-row K-loops
# speedup vs baseline: 1.0300x; 1.0009x over previous
.Lp3_loopB:
	ds_read_b128 v[148:151], v144
	ds_read_b128 v[152:155], v144 offset:1024
	ds_read_b128 v[156:159], v144 offset:2048
	ds_read_b128 v[160:163], v144 offset:3072
	ds_read_b128 v[166:169], v145
	ds_read_b128 v[170:173], v145 offset:1024
	ds_read_b128 v[174:177], v145 offset:2048
	ds_read_b128 v[178:181], v145 offset:3072
	s_add_u32 s66, s64, 0xfff92080
	s_addc_u32 s67, s65, -1
	s_cmp_eq_u32 s85, 40
	s_cselect_b32 s71, s1, s67
	s_cselect_b32 s70, s0, s66
	s_cselect_b32 s67, s63, s84
	s_cselect_b32 s66, s62, s83
	v_lshl_add_u64 v[214:215], s[64:65], 0, v[134:135]
	s_add_i32 m0, s24, 0xc000
	ds_read_b128 v[182:185], v146
	ds_read_b128 v[186:189], v146 offset:1024
	ds_read_b128 v[190:193], v146 offset:2048
	ds_read_b128 v[194:197], v146 offset:3072
	ds_read_b128 v[198:201], v146 offset:4096
	ds_read_b128 v[202:205], v146 offset:5120
	global_load_lds_dwordx4 v[214:215], off
	v_lshl_add_u64 v[214:215], s[64:65], 0, v[136:137]
	s_add_i32 m0, s24, 0xe000
	s_nop 0
	global_load_lds_dwordx4 v[214:215], off
	s_waitcnt vmcnt(8)
	s_waitcnt lgkmcnt(0)
	s_barrier
	s_waitcnt lgkmcnt(0)
	v_mfma_f32_16x16x32_bf16 v[126:129], v[148:151], v[182:185], v[126:129]
	v_mfma_f32_16x16x32_bf16 v[122:125], v[156:159], v[182:185], v[122:125]
	v_mfma_f32_16x16x32_bf16 v[126:129], v[152:155], v[186:189], v[126:129]
	v_mfma_f32_16x16x32_bf16 v[122:125], v[160:163], v[186:189], v[122:125]
	v_mfma_f32_16x16x32_bf16 v[110:113], v[166:169], v[182:185], v[110:113]
	v_mfma_f32_16x16x32_bf16 v[106:109], v[174:177], v[182:185], v[106:109]
	v_mfma_f32_16x16x32_bf16 v[110:113], v[170:173], v[186:189], v[110:113]
	v_mfma_f32_16x16x32_bf16 v[106:109], v[178:181], v[186:189], v[106:109]
	v_mfma_f32_16x16x32_bf16 v[118:121], v[148:151], v[190:193], v[118:121]
	v_mfma_f32_16x16x32_bf16 v[114:117], v[156:159], v[190:193], v[114:117]
	v_mfma_f32_16x16x32_bf16 v[118:121], v[152:155], v[194:197], v[118:121]
	v_mfma_f32_16x16x32_bf16 v[114:117], v[160:163], v[194:197], v[114:117]
	v_mfma_f32_16x16x32_bf16 v[94:97], v[166:169], v[190:193], v[94:97]
	v_mfma_f32_16x16x32_bf16 v[90:93], v[174:177], v[190:193], v[90:93]
	v_mfma_f32_16x16x32_bf16 v[94:97], v[170:173], v[194:197], v[94:97]
	v_mfma_f32_16x16x32_bf16 v[90:93], v[178:181], v[194:197], v[90:93]
	s_cmp_eq_u32 s12, 0
	s_cbranch_scc1 .Lp3_sk0
	v_mfma_f32_16x16x32_bf16 v[102:105], v[148:151], v[198:201], v[102:105]
	v_mfma_f32_16x16x32_bf16 v[98:101], v[156:159], v[198:201], v[98:101]
	v_mfma_f32_16x16x32_bf16 v[102:105], v[152:155], v[202:205], v[102:105]
	v_mfma_f32_16x16x32_bf16 v[98:101], v[160:163], v[202:205], v[98:101]
	v_mfma_f32_16x16x32_bf16 v[78:81], v[166:169], v[198:201], v[78:81]
	v_mfma_f32_16x16x32_bf16 v[74:77], v[174:177], v[198:201], v[74:77]
	v_mfma_f32_16x16x32_bf16 v[78:81], v[170:173], v[202:205], v[78:81]
	v_mfma_f32_16x16x32_bf16 v[74:77], v[178:181], v[202:205], v[74:77]
.Lp3_sk0:
	s_barrier
	s_add_i32 s86, s74, s22
	v_lshl_add_u64 v[214:215], s[66:67], 0, v[130:131]
	s_mov_b32 m0, s86
	ds_read_b128 v[182:185], v146 offset:16384
	ds_read_b128 v[186:189], v146 offset:17408
	ds_read_b128 v[190:193], v146 offset:18432
	ds_read_b128 v[194:197], v146 offset:19456
	ds_read_b128 v[198:201], v146 offset:20480
	ds_read_b128 v[202:205], v146 offset:21504
	global_load_lds_dwordx4 v[214:215], off
	s_add_i32 m0, s86, 0x2000
	s_add_u32 s86, s66, 0xb0000
	v_lshl_add_u64 v[216:217], s[66:67], 0, v[132:133]
	s_addc_u32 s87, s67, 0
	s_add_i32 s92, s75, s22
	global_load_lds_dwordx4 v[216:217], off
	v_lshl_add_u64 v[218:219], s[86:87], 0, v[130:131]
	s_mov_b32 m0, s92
	v_lshl_add_u64 v[220:221], s[70:71], 0, v[132:133]
	global_load_lds_dwordx4 v[218:219], off
	v_lshl_add_u64 v[218:219], s[86:87], 0, v[132:133]
	s_add_i32 m0, s92, 0x2000
	s_nop 0
	global_load_lds_dwordx4 v[218:219], off
	v_lshl_add_u64 v[218:219], s[70:71], 0, v[130:131]
	s_mov_b32 m0, s24
	s_nop 0
	global_load_lds_dwordx4 v[218:219], off
	s_mov_b32 m0, s25
	s_nop 0
	global_load_lds_dwordx4 v[220:221], off
	s_waitcnt vmcnt(8)
	s_waitcnt lgkmcnt(0)
	s_barrier
	s_waitcnt lgkmcnt(0)
	v_mfma_f32_16x16x32_bf16 v[62:65], v[148:151], v[182:185], v[62:65]
	v_mfma_f32_16x16x32_bf16 v[58:61], v[156:159], v[182:185], v[58:61]
	v_mfma_f32_16x16x32_bf16 v[62:65], v[152:155], v[186:189], v[62:65]
	v_mfma_f32_16x16x32_bf16 v[58:61], v[160:163], v[186:189], v[58:61]
	v_mfma_f32_16x16x32_bf16 v[46:49], v[166:169], v[182:185], v[46:49]
	v_mfma_f32_16x16x32_bf16 v[42:45], v[174:177], v[182:185], v[42:45]
	v_mfma_f32_16x16x32_bf16 v[46:49], v[170:173], v[186:189], v[46:49]
	v_mfma_f32_16x16x32_bf16 v[42:45], v[178:181], v[186:189], v[42:45]
	v_mfma_f32_16x16x32_bf16 v[54:57], v[148:151], v[190:193], v[54:57]
	v_mfma_f32_16x16x32_bf16 v[50:53], v[156:159], v[190:193], v[50:53]
	v_mfma_f32_16x16x32_bf16 v[54:57], v[152:155], v[194:197], v[54:57]
	v_mfma_f32_16x16x32_bf16 v[50:53], v[160:163], v[194:197], v[50:53]
	v_mfma_f32_16x16x32_bf16 v[30:33], v[166:169], v[190:193], v[30:33]
	v_mfma_f32_16x16x32_bf16 v[26:29], v[174:177], v[190:193], v[26:29]
	v_mfma_f32_16x16x32_bf16 v[30:33], v[170:173], v[194:197], v[30:33]
	v_mfma_f32_16x16x32_bf16 v[26:29], v[178:181], v[194:197], v[26:29]
	s_cmp_eq_u32 s12, 0
	s_cbranch_scc1 .Lp3_sk1
	v_mfma_f32_16x16x32_bf16 v[38:41], v[148:151], v[198:201], v[38:41]
	v_mfma_f32_16x16x32_bf16 v[34:37], v[156:159], v[198:201], v[34:37]
	v_mfma_f32_16x16x32_bf16 v[38:41], v[152:155], v[202:205], v[38:41]
	v_mfma_f32_16x16x32_bf16 v[34:37], v[160:163], v[202:205], v[34:37]
	v_mfma_f32_16x16x32_bf16 v[14:17], v[166:169], v[198:201], v[14:17]
	v_mfma_f32_16x16x32_bf16 v[10:13], v[174:177], v[198:201], v[10:13]
	v_mfma_f32_16x16x32_bf16 v[14:17], v[170:173], v[202:205], v[14:17]
	v_mfma_f32_16x16x32_bf16 v[10:13], v[178:181], v[202:205], v[10:13]
.Lp3_sk1:
	s_barrier
	s_add_i32 s86, 0, 0x18000
	v_add_u32_e32 v147, s86, v142
	s_add_i32 s87, 0, 0x1c000
	ds_read_b128 v[148:151], v147
	ds_read_b128 v[152:155], v147 offset:1024
	ds_read_b128 v[156:159], v147 offset:2048
	ds_read_b128 v[160:163], v147 offset:3072
	v_add_u32_e32 v147, s87, v142
	ds_read_b128 v[166:169], v147
	ds_read_b128 v[170:173], v147 offset:1024
	ds_read_b128 v[174:177], v147 offset:2048
	ds_read_b128 v[178:181], v147 offset:3072
	s_add_u32 s70, s70, 0x6e000
	s_addc_u32 s71, s71, 0
	s_mov_b32 m0, s26
	v_lshl_add_u64 v[222:223], s[70:71], 0, v[130:131]
	ds_read_b128 v[182:185], v146 offset:32768
	ds_read_b128 v[186:189], v146 offset:33792
	ds_read_b128 v[190:193], v146 offset:34816
	ds_read_b128 v[194:197], v146 offset:35840
	ds_read_b128 v[198:201], v146 offset:36864
	ds_read_b128 v[202:205], v146 offset:37888
	global_load_lds_dwordx4 v[222:223], off
	v_lshl_add_u64 v[222:223], s[70:71], 0, v[132:133]
	s_mov_b32 m0, s27
	s_nop 0
	global_load_lds_dwordx4 v[222:223], off
	s_waitcnt vmcnt(8)
	s_waitcnt lgkmcnt(0)
	s_barrier
	s_waitcnt lgkmcnt(0)
	v_mfma_f32_16x16x32_bf16 v[126:129], v[148:151], v[182:185], v[126:129]
	v_mfma_f32_16x16x32_bf16 v[122:125], v[156:159], v[182:185], v[122:125]
	v_mfma_f32_16x16x32_bf16 v[126:129], v[152:155], v[186:189], v[126:129]
	v_mfma_f32_16x16x32_bf16 v[122:125], v[160:163], v[186:189], v[122:125]
	v_mfma_f32_16x16x32_bf16 v[110:113], v[166:169], v[182:185], v[110:113]
	v_mfma_f32_16x16x32_bf16 v[106:109], v[174:177], v[182:185], v[106:109]
	v_mfma_f32_16x16x32_bf16 v[110:113], v[170:173], v[186:189], v[110:113]
	v_mfma_f32_16x16x32_bf16 v[106:109], v[178:181], v[186:189], v[106:109]
	v_mfma_f32_16x16x32_bf16 v[118:121], v[148:151], v[190:193], v[118:121]
	v_mfma_f32_16x16x32_bf16 v[114:117], v[156:159], v[190:193], v[114:117]
	v_mfma_f32_16x16x32_bf16 v[118:121], v[152:155], v[194:197], v[118:121]
	v_mfma_f32_16x16x32_bf16 v[114:117], v[160:163], v[194:197], v[114:117]
	v_mfma_f32_16x16x32_bf16 v[94:97], v[166:169], v[190:193], v[94:97]
	v_mfma_f32_16x16x32_bf16 v[90:93], v[174:177], v[190:193], v[90:93]
	v_mfma_f32_16x16x32_bf16 v[94:97], v[170:173], v[194:197], v[94:97]
	v_mfma_f32_16x16x32_bf16 v[90:93], v[178:181], v[194:197], v[90:93]
	s_cmp_eq_u32 s12, 0
	s_cbranch_scc1 .Lp3_sk2
	v_mfma_f32_16x16x32_bf16 v[102:105], v[148:151], v[198:201], v[102:105]
	v_mfma_f32_16x16x32_bf16 v[98:101], v[156:159], v[198:201], v[98:101]
	v_mfma_f32_16x16x32_bf16 v[102:105], v[152:155], v[202:205], v[102:105]
	v_mfma_f32_16x16x32_bf16 v[98:101], v[160:163], v[202:205], v[98:101]
	v_mfma_f32_16x16x32_bf16 v[78:81], v[166:169], v[198:201], v[78:81]
	v_mfma_f32_16x16x32_bf16 v[74:77], v[174:177], v[198:201], v[74:77]
	v_mfma_f32_16x16x32_bf16 v[78:81], v[170:173], v[202:205], v[78:81]
	v_mfma_f32_16x16x32_bf16 v[74:77], v[178:181], v[202:205], v[74:77]
.Lp3_sk2:
	s_barrier
	s_add_i32 s70, s86, s22
	v_lshl_add_u64 v[214:215], v[214:215], 0, s[10:11]
	s_mov_b32 m0, s70
	ds_read_b128 v[182:185], v146 offset:49152
	ds_read_b128 v[186:189], v146 offset:50176
	ds_read_b128 v[190:193], v146 offset:51200
	ds_read_b128 v[194:197], v146 offset:52224
	ds_read_b128 v[198:201], v146 offset:53248
	ds_read_b128 v[202:205], v146 offset:54272
	global_load_lds_dwordx4 v[214:215], off
	s_add_i32 m0, s70, 0x2000
	s_add_u32 s66, s66, 0xb0080
	v_lshl_add_u64 v[214:215], v[216:217], 0, s[10:11]
	s_addc_u32 s67, s67, 0
	s_add_i32 s70, s87, s22
	global_load_lds_dwordx4 v[214:215], off
	v_lshl_add_u64 v[214:215], s[66:67], 0, v[130:131]
	s_mov_b32 m0, s70
	s_nop 0
	global_load_lds_dwordx4 v[214:215], off
	v_lshl_add_u64 v[214:215], s[66:67], 0, v[132:133]
	s_add_i32 m0, s70, 0x2000
	s_nop 0
	global_load_lds_dwordx4 v[214:215], off
	v_lshl_add_u64 v[214:215], v[218:219], 0, s[10:11]
	s_mov_b32 m0, s72
	s_nop 0
	global_load_lds_dwordx4 v[214:215], off
	v_lshl_add_u64 v[214:215], v[220:221], 0, s[10:11]
	s_mov_b32 m0, s73
	s_nop 0
	global_load_lds_dwordx4 v[214:215], off
	s_waitcnt vmcnt(8)
	s_waitcnt lgkmcnt(0)
	s_barrier
	s_waitcnt lgkmcnt(0)
	v_mfma_f32_16x16x32_bf16 v[62:65], v[148:151], v[182:185], v[62:65]
	v_mfma_f32_16x16x32_bf16 v[58:61], v[156:159], v[182:185], v[58:61]
	v_mfma_f32_16x16x32_bf16 v[62:65], v[152:155], v[186:189], v[62:65]
	v_mfma_f32_16x16x32_bf16 v[58:61], v[160:163], v[186:189], v[58:61]
	v_mfma_f32_16x16x32_bf16 v[46:49], v[166:169], v[182:185], v[46:49]
	v_mfma_f32_16x16x32_bf16 v[42:45], v[174:177], v[182:185], v[42:45]
	v_mfma_f32_16x16x32_bf16 v[46:49], v[170:173], v[186:189], v[46:49]
	v_mfma_f32_16x16x32_bf16 v[42:45], v[178:181], v[186:189], v[42:45]
	v_mfma_f32_16x16x32_bf16 v[54:57], v[148:151], v[190:193], v[54:57]
	v_mfma_f32_16x16x32_bf16 v[50:53], v[156:159], v[190:193], v[50:53]
	v_mfma_f32_16x16x32_bf16 v[54:57], v[152:155], v[194:197], v[54:57]
	v_mfma_f32_16x16x32_bf16 v[50:53], v[160:163], v[194:197], v[50:53]
	v_mfma_f32_16x16x32_bf16 v[30:33], v[166:169], v[190:193], v[30:33]
	v_mfma_f32_16x16x32_bf16 v[26:29], v[174:177], v[190:193], v[26:29]
	v_mfma_f32_16x16x32_bf16 v[30:33], v[170:173], v[194:197], v[30:33]
	v_mfma_f32_16x16x32_bf16 v[26:29], v[178:181], v[194:197], v[26:29]
	s_cmp_eq_u32 s12, 0
	s_cbranch_scc1 .Lp3_sk3
	v_mfma_f32_16x16x32_bf16 v[38:41], v[148:151], v[198:201], v[38:41]
	v_mfma_f32_16x16x32_bf16 v[34:37], v[156:159], v[198:201], v[34:37]
	v_mfma_f32_16x16x32_bf16 v[38:41], v[152:155], v[202:205], v[38:41]
	v_mfma_f32_16x16x32_bf16 v[34:37], v[160:163], v[202:205], v[34:37]
	v_mfma_f32_16x16x32_bf16 v[14:17], v[166:169], v[198:201], v[14:17]
	v_mfma_f32_16x16x32_bf16 v[10:13], v[174:177], v[198:201], v[10:13]
	v_mfma_f32_16x16x32_bf16 v[14:17], v[170:173], v[202:205], v[14:17]
	v_mfma_f32_16x16x32_bf16 v[10:13], v[178:181], v[202:205], v[10:13]
.Lp3_sk3:
	s_barrier
	s_add_i32 s85, s85, 2
	s_add_u32 s64, s64, 0x100
	s_addc_u32 s65, s65, 0
	s_add_u32 s83, s83, 0x100
	s_addc_u32 s84, s84, 0
	s_cmp_gt_u32 s85, 41
	s_cbranch_scc0 .Lp3_loopB
	s_branch .Lp3_loopX
.Lp3_loopA:
	ds_read_b128 v[148:151], v144
	ds_read_b128 v[152:155], v144 offset:1024
	ds_read_b128 v[156:159], v144 offset:2048
	ds_read_b128 v[160:163], v144 offset:3072
	ds_read_b128 v[166:169], v145
	ds_read_b128 v[170:173], v145 offset:1024
	ds_read_b128 v[174:177], v145 offset:2048
	ds_read_b128 v[178:181], v145 offset:3072
	s_add_u32 s66, s64, 0xfff92080
	s_addc_u32 s67, s65, -1
	s_cmp_eq_u32 s85, 40
	s_cselect_b32 s71, s1, s67
	s_cselect_b32 s70, s0, s66
	s_cselect_b32 s67, s63, s84
	s_cselect_b32 s66, s62, s83
	v_lshl_add_u64 v[214:215], s[64:65], 0, v[134:135]
	ds_read_b128 v[182:185], v146
	ds_read_b128 v[186:189], v146 offset:1024
	ds_read_b128 v[190:193], v146 offset:2048
	ds_read_b128 v[194:197], v146 offset:3072
	ds_read_b128 v[198:201], v146 offset:4096
	ds_read_b128 v[202:205], v146 offset:5120
	v_lshl_add_u64 v[214:215], s[64:65], 0, v[136:137]
	s_add_i32 m0, s24, 0xe000
	s_nop 0
	global_load_lds_dwordx4 v[214:215], off
	s_waitcnt vmcnt(6)
	s_waitcnt lgkmcnt(0)
	s_barrier
	s_waitcnt lgkmcnt(0)
	v_mfma_f32_16x16x32_bf16 v[126:129], v[148:151], v[182:185], v[126:129]
	v_mfma_f32_16x16x32_bf16 v[122:125], v[156:159], v[182:185], v[122:125]
	v_mfma_f32_16x16x32_bf16 v[126:129], v[152:155], v[186:189], v[126:129]
	v_mfma_f32_16x16x32_bf16 v[122:125], v[160:163], v[186:189], v[122:125]
	v_mfma_f32_16x16x32_bf16 v[110:113], v[166:169], v[182:185], v[110:113]
	v_mfma_f32_16x16x32_bf16 v[106:109], v[174:177], v[182:185], v[106:109]
	v_mfma_f32_16x16x32_bf16 v[110:113], v[170:173], v[186:189], v[110:113]
	v_mfma_f32_16x16x32_bf16 v[106:109], v[178:181], v[186:189], v[106:109]
	v_mfma_f32_16x16x32_bf16 v[118:121], v[148:151], v[190:193], v[118:121]
	v_mfma_f32_16x16x32_bf16 v[114:117], v[156:159], v[190:193], v[114:117]
	v_mfma_f32_16x16x32_bf16 v[118:121], v[152:155], v[194:197], v[118:121]
	v_mfma_f32_16x16x32_bf16 v[114:117], v[160:163], v[194:197], v[114:117]
	v_mfma_f32_16x16x32_bf16 v[94:97], v[166:169], v[190:193], v[94:97]
	v_mfma_f32_16x16x32_bf16 v[90:93], v[174:177], v[190:193], v[90:93]
	v_mfma_f32_16x16x32_bf16 v[94:97], v[170:173], v[194:197], v[94:97]
	v_mfma_f32_16x16x32_bf16 v[90:93], v[178:181], v[194:197], v[90:93]
	s_cmp_eq_u32 s12, 0
	s_cbranch_scc1 .Lp3_skA0
	v_mfma_f32_16x16x32_bf16 v[102:105], v[148:151], v[198:201], v[102:105]
	v_mfma_f32_16x16x32_bf16 v[98:101], v[156:159], v[198:201], v[98:101]
	v_mfma_f32_16x16x32_bf16 v[102:105], v[152:155], v[202:205], v[102:105]
	v_mfma_f32_16x16x32_bf16 v[98:101], v[160:163], v[202:205], v[98:101]
	v_mfma_f32_16x16x32_bf16 v[78:81], v[166:169], v[198:201], v[78:81]
	v_mfma_f32_16x16x32_bf16 v[74:77], v[174:177], v[198:201], v[74:77]
	v_mfma_f32_16x16x32_bf16 v[78:81], v[170:173], v[202:205], v[78:81]
	v_mfma_f32_16x16x32_bf16 v[74:77], v[178:181], v[202:205], v[74:77]
.Lp3_skA0:
	s_barrier
	s_add_i32 s86, s74, s22
	v_lshl_add_u64 v[214:215], s[66:67], 0, v[130:131]
	s_mov_b32 m0, s86
	ds_read_b128 v[182:185], v146 offset:16384
	ds_read_b128 v[186:189], v146 offset:17408
	ds_read_b128 v[190:193], v146 offset:18432
	ds_read_b128 v[194:197], v146 offset:19456
	ds_read_b128 v[198:201], v146 offset:20480
	ds_read_b128 v[202:205], v146 offset:21504
	global_load_lds_dwordx4 v[214:215], off
	s_add_i32 m0, s86, 0x2000
	s_add_u32 s86, s66, 0xb0000
	v_lshl_add_u64 v[216:217], s[66:67], 0, v[132:133]
	s_addc_u32 s87, s67, 0
	s_add_i32 s92, s75, s22
	global_load_lds_dwordx4 v[216:217], off
	v_lshl_add_u64 v[218:219], s[86:87], 0, v[130:131]
	s_mov_b32 m0, s92
	v_lshl_add_u64 v[220:221], s[70:71], 0, v[132:133]
	global_load_lds_dwordx4 v[218:219], off
	v_lshl_add_u64 v[218:219], s[86:87], 0, v[132:133]
	s_add_i32 m0, s92, 0x2000
	s_nop 0
	global_load_lds_dwordx4 v[218:219], off
	v_lshl_add_u64 v[218:219], s[70:71], 0, v[130:131]
	s_nop 0
	s_mov_b32 m0, s25
	s_nop 0
	global_load_lds_dwordx4 v[220:221], off
	s_waitcnt vmcnt(6)
	s_waitcnt lgkmcnt(0)
	s_barrier
	s_waitcnt lgkmcnt(0)
	v_mfma_f32_16x16x32_bf16 v[62:65], v[148:151], v[182:185], v[62:65]
	v_mfma_f32_16x16x32_bf16 v[58:61], v[156:159], v[182:185], v[58:61]
	v_mfma_f32_16x16x32_bf16 v[62:65], v[152:155], v[186:189], v[62:65]
	v_mfma_f32_16x16x32_bf16 v[58:61], v[160:163], v[186:189], v[58:61]
	v_mfma_f32_16x16x32_bf16 v[46:49], v[166:169], v[182:185], v[46:49]
	v_mfma_f32_16x16x32_bf16 v[42:45], v[174:177], v[182:185], v[42:45]
	v_mfma_f32_16x16x32_bf16 v[46:49], v[170:173], v[186:189], v[46:49]
	v_mfma_f32_16x16x32_bf16 v[42:45], v[178:181], v[186:189], v[42:45]
	v_mfma_f32_16x16x32_bf16 v[54:57], v[148:151], v[190:193], v[54:57]
	v_mfma_f32_16x16x32_bf16 v[50:53], v[156:159], v[190:193], v[50:53]
	v_mfma_f32_16x16x32_bf16 v[54:57], v[152:155], v[194:197], v[54:57]
	v_mfma_f32_16x16x32_bf16 v[50:53], v[160:163], v[194:197], v[50:53]
	v_mfma_f32_16x16x32_bf16 v[30:33], v[166:169], v[190:193], v[30:33]
	v_mfma_f32_16x16x32_bf16 v[26:29], v[174:177], v[190:193], v[26:29]
	v_mfma_f32_16x16x32_bf16 v[30:33], v[170:173], v[194:197], v[30:33]
	v_mfma_f32_16x16x32_bf16 v[26:29], v[178:181], v[194:197], v[26:29]
	s_cmp_eq_u32 s12, 0
	s_cbranch_scc1 .Lp3_skA1
	v_mfma_f32_16x16x32_bf16 v[38:41], v[148:151], v[198:201], v[38:41]
	v_mfma_f32_16x16x32_bf16 v[34:37], v[156:159], v[198:201], v[34:37]
	v_mfma_f32_16x16x32_bf16 v[38:41], v[152:155], v[202:205], v[38:41]
	v_mfma_f32_16x16x32_bf16 v[34:37], v[160:163], v[202:205], v[34:37]
	v_mfma_f32_16x16x32_bf16 v[14:17], v[166:169], v[198:201], v[14:17]
	v_mfma_f32_16x16x32_bf16 v[10:13], v[174:177], v[198:201], v[10:13]
	v_mfma_f32_16x16x32_bf16 v[14:17], v[170:173], v[202:205], v[14:17]
	v_mfma_f32_16x16x32_bf16 v[10:13], v[178:181], v[202:205], v[10:13]
.Lp3_skA1:
	s_barrier
	s_add_i32 s86, 0, 0x18000
	v_add_u32_e32 v147, s86, v142
	s_add_i32 s87, 0, 0x1c000
	ds_read_b128 v[148:151], v147
	ds_read_b128 v[152:155], v147 offset:1024
	ds_read_b128 v[156:159], v147 offset:2048
	ds_read_b128 v[160:163], v147 offset:3072
	v_add_u32_e32 v147, s87, v142
	ds_read_b128 v[166:169], v147
	ds_read_b128 v[170:173], v147 offset:1024
	ds_read_b128 v[174:177], v147 offset:2048
	ds_read_b128 v[178:181], v147 offset:3072
	s_add_u32 s70, s70, 0x6e000
	s_addc_u32 s71, s71, 0
	v_lshl_add_u64 v[222:223], s[70:71], 0, v[130:131]
	ds_read_b128 v[182:185], v146 offset:32768
	ds_read_b128 v[186:189], v146 offset:33792
	ds_read_b128 v[190:193], v146 offset:34816
	ds_read_b128 v[194:197], v146 offset:35840
	ds_read_b128 v[198:201], v146 offset:36864
	ds_read_b128 v[202:205], v146 offset:37888
	v_lshl_add_u64 v[222:223], s[70:71], 0, v[132:133]
	s_mov_b32 m0, s27
	s_nop 0
	global_load_lds_dwordx4 v[222:223], off
	s_waitcnt vmcnt(6)
	s_waitcnt lgkmcnt(0)
	s_barrier
	s_waitcnt lgkmcnt(0)
	v_mfma_f32_16x16x32_bf16 v[126:129], v[148:151], v[182:185], v[126:129]
	v_mfma_f32_16x16x32_bf16 v[122:125], v[156:159], v[182:185], v[122:125]
	v_mfma_f32_16x16x32_bf16 v[126:129], v[152:155], v[186:189], v[126:129]
	v_mfma_f32_16x16x32_bf16 v[122:125], v[160:163], v[186:189], v[122:125]
	v_mfma_f32_16x16x32_bf16 v[110:113], v[166:169], v[182:185], v[110:113]
	v_mfma_f32_16x16x32_bf16 v[106:109], v[174:177], v[182:185], v[106:109]
	v_mfma_f32_16x16x32_bf16 v[110:113], v[170:173], v[186:189], v[110:113]
	v_mfma_f32_16x16x32_bf16 v[106:109], v[178:181], v[186:189], v[106:109]
	v_mfma_f32_16x16x32_bf16 v[118:121], v[148:151], v[190:193], v[118:121]
	v_mfma_f32_16x16x32_bf16 v[114:117], v[156:159], v[190:193], v[114:117]
	v_mfma_f32_16x16x32_bf16 v[118:121], v[152:155], v[194:197], v[118:121]
	v_mfma_f32_16x16x32_bf16 v[114:117], v[160:163], v[194:197], v[114:117]
	v_mfma_f32_16x16x32_bf16 v[94:97], v[166:169], v[190:193], v[94:97]
	v_mfma_f32_16x16x32_bf16 v[90:93], v[174:177], v[190:193], v[90:93]
	v_mfma_f32_16x16x32_bf16 v[94:97], v[170:173], v[194:197], v[94:97]
	v_mfma_f32_16x16x32_bf16 v[90:93], v[178:181], v[194:197], v[90:93]
	s_cmp_eq_u32 s12, 0
	s_cbranch_scc1 .Lp3_skA2
	v_mfma_f32_16x16x32_bf16 v[102:105], v[148:151], v[198:201], v[102:105]
	v_mfma_f32_16x16x32_bf16 v[98:101], v[156:159], v[198:201], v[98:101]
	v_mfma_f32_16x16x32_bf16 v[102:105], v[152:155], v[202:205], v[102:105]
	v_mfma_f32_16x16x32_bf16 v[98:101], v[160:163], v[202:205], v[98:101]
	v_mfma_f32_16x16x32_bf16 v[78:81], v[166:169], v[198:201], v[78:81]
	v_mfma_f32_16x16x32_bf16 v[74:77], v[174:177], v[198:201], v[74:77]
	v_mfma_f32_16x16x32_bf16 v[78:81], v[170:173], v[202:205], v[78:81]
	v_mfma_f32_16x16x32_bf16 v[74:77], v[178:181], v[202:205], v[74:77]
.Lp3_skA2:
	s_barrier
	s_add_i32 s70, s86, s22
	v_lshl_add_u64 v[214:215], v[214:215], 0, s[10:11]
	s_mov_b32 m0, s70
	ds_read_b128 v[182:185], v146 offset:49152
	ds_read_b128 v[186:189], v146 offset:50176
	ds_read_b128 v[190:193], v146 offset:51200
	ds_read_b128 v[194:197], v146 offset:52224
	ds_read_b128 v[198:201], v146 offset:53248
	ds_read_b128 v[202:205], v146 offset:54272
	global_load_lds_dwordx4 v[214:215], off
	s_add_i32 m0, s70, 0x2000
	s_add_u32 s66, s66, 0xb0080
	v_lshl_add_u64 v[214:215], v[216:217], 0, s[10:11]
	s_addc_u32 s67, s67, 0
	s_add_i32 s70, s87, s22
	global_load_lds_dwordx4 v[214:215], off
	v_lshl_add_u64 v[214:215], s[66:67], 0, v[130:131]
	s_mov_b32 m0, s70
	s_nop 0
	global_load_lds_dwordx4 v[214:215], off
	v_lshl_add_u64 v[214:215], s[66:67], 0, v[132:133]
	s_add_i32 m0, s70, 0x2000
	s_nop 0
	global_load_lds_dwordx4 v[214:215], off
	v_lshl_add_u64 v[214:215], v[218:219], 0, s[10:11]
	s_nop 0
	v_lshl_add_u64 v[214:215], v[220:221], 0, s[10:11]
	s_mov_b32 m0, s73
	s_nop 0
	global_load_lds_dwordx4 v[214:215], off
	s_waitcnt vmcnt(6)
	s_waitcnt lgkmcnt(0)
	s_barrier
	s_waitcnt lgkmcnt(0)
	v_mfma_f32_16x16x32_bf16 v[62:65], v[148:151], v[182:185], v[62:65]
	v_mfma_f32_16x16x32_bf16 v[58:61], v[156:159], v[182:185], v[58:61]
	v_mfma_f32_16x16x32_bf16 v[62:65], v[152:155], v[186:189], v[62:65]
	v_mfma_f32_16x16x32_bf16 v[58:61], v[160:163], v[186:189], v[58:61]
	v_mfma_f32_16x16x32_bf16 v[46:49], v[166:169], v[182:185], v[46:49]
	v_mfma_f32_16x16x32_bf16 v[42:45], v[174:177], v[182:185], v[42:45]
	v_mfma_f32_16x16x32_bf16 v[46:49], v[170:173], v[186:189], v[46:49]
	v_mfma_f32_16x16x32_bf16 v[42:45], v[178:181], v[186:189], v[42:45]
	v_mfma_f32_16x16x32_bf16 v[54:57], v[148:151], v[190:193], v[54:57]
	v_mfma_f32_16x16x32_bf16 v[50:53], v[156:159], v[190:193], v[50:53]
	v_mfma_f32_16x16x32_bf16 v[54:57], v[152:155], v[194:197], v[54:57]
	v_mfma_f32_16x16x32_bf16 v[50:53], v[160:163], v[194:197], v[50:53]
	v_mfma_f32_16x16x32_bf16 v[30:33], v[166:169], v[190:193], v[30:33]
	v_mfma_f32_16x16x32_bf16 v[26:29], v[174:177], v[190:193], v[26:29]
	v_mfma_f32_16x16x32_bf16 v[30:33], v[170:173], v[194:197], v[30:33]
	v_mfma_f32_16x16x32_bf16 v[26:29], v[178:181], v[194:197], v[26:29]
	s_cmp_eq_u32 s12, 0
	s_cbranch_scc1 .Lp3_skA3
	v_mfma_f32_16x16x32_bf16 v[38:41], v[148:151], v[198:201], v[38:41]
	v_mfma_f32_16x16x32_bf16 v[34:37], v[156:159], v[198:201], v[34:37]
	v_mfma_f32_16x16x32_bf16 v[38:41], v[152:155], v[202:205], v[38:41]
	v_mfma_f32_16x16x32_bf16 v[34:37], v[160:163], v[202:205], v[34:37]
	v_mfma_f32_16x16x32_bf16 v[14:17], v[166:169], v[198:201], v[14:17]
	v_mfma_f32_16x16x32_bf16 v[10:13], v[174:177], v[198:201], v[10:13]
	v_mfma_f32_16x16x32_bf16 v[14:17], v[170:173], v[202:205], v[14:17]
	v_mfma_f32_16x16x32_bf16 v[10:13], v[178:181], v[202:205], v[10:13]
.Lp3_skA3:
	s_barrier
	s_add_i32 s85, s85, 2
	s_add_u32 s64, s64, 0x100
	s_addc_u32 s65, s65, 0
	s_add_u32 s83, s83, 0x100
	s_addc_u32 s84, s84, 0
	s_cmp_gt_u32 s85, 41
	s_cbranch_scc0 .Lp3_loopA

.Lp7_loopB:
	ds_read_b128 v[148:151], v144
	ds_read_b128 v[152:155], v144 offset:1024
	ds_read_b128 v[156:159], v144 offset:2048
	ds_read_b128 v[160:163], v144 offset:3072
	ds_read_b128 v[166:169], v145
	ds_read_b128 v[170:173], v145 offset:1024
	ds_read_b128 v[174:177], v145 offset:2048
	ds_read_b128 v[178:181], v145 offset:3072
	s_add_u32 s52, s50, 0xfffd8080
	s_addc_u32 s53, s51, -1
	s_cmp_eq_u32 s78, 12
	s_cselect_b32 s55, s45, s53
	s_cselect_b32 s54, s74, s52
	s_cselect_b32 s53, s23, s77
	s_cselect_b32 s52, s75, s76
	v_lshl_add_u64 v[214:215], s[50:51], 0, v[134:135]
	s_add_i32 m0, s25, 0xc000
	ds_read_b128 v[182:185], v146
	ds_read_b128 v[186:189], v146 offset:1024
	ds_read_b128 v[190:193], v146 offset:2048
	ds_read_b128 v[194:197], v146 offset:3072
	ds_read_b128 v[198:201], v146 offset:4096
	ds_read_b128 v[202:205], v146 offset:5120
	global_load_lds_dwordx4 v[214:215], off
	v_lshl_add_u64 v[214:215], s[50:51], 0, v[136:137]
	s_add_i32 m0, s25, 0xe000
	s_nop 0
	global_load_lds_dwordx4 v[214:215], off
	s_waitcnt vmcnt(8)
	s_waitcnt lgkmcnt(0)
	s_barrier
	s_waitcnt lgkmcnt(0)
	v_mfma_f32_16x16x32_bf16 v[126:129], v[148:151], v[182:185], v[126:129]
	v_mfma_f32_16x16x32_bf16 v[122:125], v[156:159], v[182:185], v[122:125]
	v_mfma_f32_16x16x32_bf16 v[126:129], v[152:155], v[186:189], v[126:129]
	v_mfma_f32_16x16x32_bf16 v[122:125], v[160:163], v[186:189], v[122:125]
	v_mfma_f32_16x16x32_bf16 v[110:113], v[166:169], v[182:185], v[110:113]
	v_mfma_f32_16x16x32_bf16 v[106:109], v[174:177], v[182:185], v[106:109]
	v_mfma_f32_16x16x32_bf16 v[110:113], v[170:173], v[186:189], v[110:113]
	v_mfma_f32_16x16x32_bf16 v[106:109], v[178:181], v[186:189], v[106:109]
	v_mfma_f32_16x16x32_bf16 v[118:121], v[148:151], v[190:193], v[118:121]
	v_mfma_f32_16x16x32_bf16 v[114:117], v[156:159], v[190:193], v[114:117]
	v_mfma_f32_16x16x32_bf16 v[118:121], v[152:155], v[194:197], v[118:121]
	v_mfma_f32_16x16x32_bf16 v[114:117], v[160:163], v[194:197], v[114:117]
	v_mfma_f32_16x16x32_bf16 v[94:97], v[166:169], v[190:193], v[94:97]
	v_mfma_f32_16x16x32_bf16 v[90:93], v[174:177], v[190:193], v[90:93]
	v_mfma_f32_16x16x32_bf16 v[94:97], v[170:173], v[194:197], v[94:97]
	v_mfma_f32_16x16x32_bf16 v[90:93], v[178:181], v[194:197], v[90:93]
	s_cmp_eq_u32 s12, 0
	s_cbranch_scc1 .Lp7_sk0
	v_mfma_f32_16x16x32_bf16 v[102:105], v[148:151], v[198:201], v[102:105]
	v_mfma_f32_16x16x32_bf16 v[98:101], v[156:159], v[198:201], v[98:101]
	v_mfma_f32_16x16x32_bf16 v[102:105], v[152:155], v[202:205], v[102:105]
	v_mfma_f32_16x16x32_bf16 v[98:101], v[160:163], v[202:205], v[98:101]
	v_mfma_f32_16x16x32_bf16 v[78:81], v[166:169], v[198:201], v[78:81]
	v_mfma_f32_16x16x32_bf16 v[74:77], v[174:177], v[198:201], v[74:77]
	v_mfma_f32_16x16x32_bf16 v[78:81], v[170:173], v[202:205], v[78:81]
	v_mfma_f32_16x16x32_bf16 v[74:77], v[178:181], v[202:205], v[74:77]
.Lp7_sk0:
	s_barrier
	s_add_i32 s79, s67, s58
	v_lshl_add_u64 v[214:215], s[52:53], 0, v[130:131]
	s_mov_b32 m0, s79
	ds_read_b128 v[182:185], v146 offset:16384
	ds_read_b128 v[186:189], v146 offset:17408
	ds_read_b128 v[190:193], v146 offset:18432
	ds_read_b128 v[194:197], v146 offset:19456
	ds_read_b128 v[198:201], v146 offset:20480
	ds_read_b128 v[202:205], v146 offset:21504
	global_load_lds_dwordx4 v[214:215], off
	s_add_i32 m0, s79, 0x2000
	s_add_u32 s80, s52, 0x40000
	v_lshl_add_u64 v[216:217], s[52:53], 0, v[132:133]
	s_addc_u32 s81, s53, 0
	s_add_i32 s79, s68, s58
	global_load_lds_dwordx4 v[216:217], off
	v_lshl_add_u64 v[218:219], s[80:81], 0, v[130:131]
	s_mov_b32 m0, s79
	v_lshl_add_u64 v[220:221], s[54:55], 0, v[132:133]
	global_load_lds_dwordx4 v[218:219], off
	v_lshl_add_u64 v[218:219], s[80:81], 0, v[132:133]
	s_add_i32 m0, s79, 0x2000
	s_nop 0
	global_load_lds_dwordx4 v[218:219], off
	v_lshl_add_u64 v[218:219], s[54:55], 0, v[130:131]
	s_mov_b32 m0, s25
	s_nop 0
	global_load_lds_dwordx4 v[218:219], off
	s_mov_b32 m0, s60
	s_nop 0
	global_load_lds_dwordx4 v[220:221], off
	s_waitcnt vmcnt(8)
	s_waitcnt lgkmcnt(0)
	s_barrier
	s_waitcnt lgkmcnt(0)
	v_mfma_f32_16x16x32_bf16 v[62:65], v[148:151], v[182:185], v[62:65]
	v_mfma_f32_16x16x32_bf16 v[58:61], v[156:159], v[182:185], v[58:61]
	v_mfma_f32_16x16x32_bf16 v[62:65], v[152:155], v[186:189], v[62:65]
	v_mfma_f32_16x16x32_bf16 v[58:61], v[160:163], v[186:189], v[58:61]
	v_mfma_f32_16x16x32_bf16 v[46:49], v[166:169], v[182:185], v[46:49]
	v_mfma_f32_16x16x32_bf16 v[42:45], v[174:177], v[182:185], v[42:45]
	v_mfma_f32_16x16x32_bf16 v[46:49], v[170:173], v[186:189], v[46:49]
	v_mfma_f32_16x16x32_bf16 v[42:45], v[178:181], v[186:189], v[42:45]
	v_mfma_f32_16x16x32_bf16 v[54:57], v[148:151], v[190:193], v[54:57]
	v_mfma_f32_16x16x32_bf16 v[50:53], v[156:159], v[190:193], v[50:53]
	v_mfma_f32_16x16x32_bf16 v[54:57], v[152:155], v[194:197], v[54:57]
	v_mfma_f32_16x16x32_bf16 v[50:53], v[160:163], v[194:197], v[50:53]
	v_mfma_f32_16x16x32_bf16 v[30:33], v[166:169], v[190:193], v[30:33]
	v_mfma_f32_16x16x32_bf16 v[26:29], v[174:177], v[190:193], v[26:29]
	v_mfma_f32_16x16x32_bf16 v[30:33], v[170:173], v[194:197], v[30:33]
	v_mfma_f32_16x16x32_bf16 v[26:29], v[178:181], v[194:197], v[26:29]
	s_cmp_eq_u32 s12, 0
	s_cbranch_scc1 .Lp7_sk1
	v_mfma_f32_16x16x32_bf16 v[38:41], v[148:151], v[198:201], v[38:41]
	v_mfma_f32_16x16x32_bf16 v[34:37], v[156:159], v[198:201], v[34:37]
	v_mfma_f32_16x16x32_bf16 v[38:41], v[152:155], v[202:205], v[38:41]
	v_mfma_f32_16x16x32_bf16 v[34:37], v[160:163], v[202:205], v[34:37]
	v_mfma_f32_16x16x32_bf16 v[14:17], v[166:169], v[198:201], v[14:17]
	v_mfma_f32_16x16x32_bf16 v[10:13], v[174:177], v[198:201], v[10:13]
	v_mfma_f32_16x16x32_bf16 v[14:17], v[170:173], v[202:205], v[14:17]
	v_mfma_f32_16x16x32_bf16 v[10:13], v[178:181], v[202:205], v[10:13]
.Lp7_sk1:
	s_barrier
	s_add_i32 s79, 0, 0x18000
	v_add_u32_e32 v147, s79, v142
	s_add_i32 s80, 0, 0x1c000
	ds_read_b128 v[148:151], v147
	ds_read_b128 v[152:155], v147 offset:1024
	ds_read_b128 v[156:159], v147 offset:2048
	ds_read_b128 v[160:163], v147 offset:3072
	v_add_u32_e32 v147, s80, v142
	ds_read_b128 v[166:169], v147
	ds_read_b128 v[170:173], v147 offset:1024
	ds_read_b128 v[174:177], v147 offset:2048
	ds_read_b128 v[178:181], v147 offset:3072
	s_add_u32 s54, s54, 0x28000
	s_addc_u32 s55, s55, 0
	s_mov_b32 m0, s61
	v_lshl_add_u64 v[222:223], s[54:55], 0, v[130:131]
	ds_read_b128 v[182:185], v146 offset:32768
	ds_read_b128 v[186:189], v146 offset:33792
	ds_read_b128 v[190:193], v146 offset:34816
	ds_read_b128 v[194:197], v146 offset:35840
	ds_read_b128 v[198:201], v146 offset:36864
	ds_read_b128 v[202:205], v146 offset:37888
	global_load_lds_dwordx4 v[222:223], off
	v_lshl_add_u64 v[222:223], s[54:55], 0, v[132:133]
	s_mov_b32 m0, s62
	s_nop 0
	global_load_lds_dwordx4 v[222:223], off
	s_waitcnt vmcnt(8)
	s_waitcnt lgkmcnt(0)
	s_barrier
	s_waitcnt lgkmcnt(0)
	v_mfma_f32_16x16x32_bf16 v[126:129], v[148:151], v[182:185], v[126:129]
	v_mfma_f32_16x16x32_bf16 v[122:125], v[156:159], v[182:185], v[122:125]
	v_mfma_f32_16x16x32_bf16 v[126:129], v[152:155], v[186:189], v[126:129]
	v_mfma_f32_16x16x32_bf16 v[122:125], v[160:163], v[186:189], v[122:125]
	v_mfma_f32_16x16x32_bf16 v[110:113], v[166:169], v[182:185], v[110:113]
	v_mfma_f32_16x16x32_bf16 v[106:109], v[174:177], v[182:185], v[106:109]
	v_mfma_f32_16x16x32_bf16 v[110:113], v[170:173], v[186:189], v[110:113]
	v_mfma_f32_16x16x32_bf16 v[106:109], v[178:181], v[186:189], v[106:109]
	v_mfma_f32_16x16x32_bf16 v[118:121], v[148:151], v[190:193], v[118:121]
	v_mfma_f32_16x16x32_bf16 v[114:117], v[156:159], v[190:193], v[114:117]
	v_mfma_f32_16x16x32_bf16 v[118:121], v[152:155], v[194:197], v[118:121]
	v_mfma_f32_16x16x32_bf16 v[114:117], v[160:163], v[194:197], v[114:117]
	v_mfma_f32_16x16x32_bf16 v[94:97], v[166:169], v[190:193], v[94:97]
	v_mfma_f32_16x16x32_bf16 v[90:93], v[174:177], v[190:193], v[90:93]
	v_mfma_f32_16x16x32_bf16 v[94:97], v[170:173], v[194:197], v[94:97]
	v_mfma_f32_16x16x32_bf16 v[90:93], v[178:181], v[194:197], v[90:93]
	s_cmp_eq_u32 s12, 0
	s_cbranch_scc1 .Lp7_sk2
	v_mfma_f32_16x16x32_bf16 v[102:105], v[148:151], v[198:201], v[102:105]
	v_mfma_f32_16x16x32_bf16 v[98:101], v[156:159], v[198:201], v[98:101]
	v_mfma_f32_16x16x32_bf16 v[102:105], v[152:155], v[202:205], v[102:105]
	v_mfma_f32_16x16x32_bf16 v[98:101], v[160:163], v[202:205], v[98:101]
	v_mfma_f32_16x16x32_bf16 v[78:81], v[166:169], v[198:201], v[78:81]
	v_mfma_f32_16x16x32_bf16 v[74:77], v[174:177], v[198:201], v[74:77]
	v_mfma_f32_16x16x32_bf16 v[78:81], v[170:173], v[202:205], v[78:81]
	v_mfma_f32_16x16x32_bf16 v[74:77], v[178:181], v[202:205], v[74:77]
.Lp7_sk2:
	s_barrier
	s_add_i32 s54, s79, s58
	v_lshl_add_u64 v[214:215], v[214:215], 0, s[10:11]
	s_mov_b32 m0, s54
	ds_read_b128 v[182:185], v146 offset:49152
	ds_read_b128 v[186:189], v146 offset:50176
	ds_read_b128 v[190:193], v146 offset:51200
	ds_read_b128 v[194:197], v146 offset:52224
	ds_read_b128 v[198:201], v146 offset:53248
	ds_read_b128 v[202:205], v146 offset:54272
	global_load_lds_dwordx4 v[214:215], off
	s_add_i32 m0, s54, 0x2000
	s_add_u32 s52, s52, 0x40080
	v_lshl_add_u64 v[214:215], v[216:217], 0, s[10:11]
	s_addc_u32 s53, s53, 0
	s_add_i32 s54, s80, s58
	global_load_lds_dwordx4 v[214:215], off
	v_lshl_add_u64 v[214:215], s[52:53], 0, v[130:131]
	s_mov_b32 m0, s54
	s_nop 0
	global_load_lds_dwordx4 v[214:215], off
	v_lshl_add_u64 v[214:215], s[52:53], 0, v[132:133]
	s_add_i32 m0, s54, 0x2000
	s_nop 0
	global_load_lds_dwordx4 v[214:215], off
	v_lshl_add_u64 v[214:215], v[218:219], 0, s[10:11]
	s_mov_b32 m0, s65
	s_nop 0
	global_load_lds_dwordx4 v[214:215], off
	v_lshl_add_u64 v[214:215], v[220:221], 0, s[10:11]
	s_mov_b32 m0, s66
	s_nop 0
	global_load_lds_dwordx4 v[214:215], off
	s_waitcnt vmcnt(8)
	s_waitcnt lgkmcnt(0)
	s_barrier
	s_waitcnt lgkmcnt(0)
	v_mfma_f32_16x16x32_bf16 v[62:65], v[148:151], v[182:185], v[62:65]
	v_mfma_f32_16x16x32_bf16 v[58:61], v[156:159], v[182:185], v[58:61]
	v_mfma_f32_16x16x32_bf16 v[62:65], v[152:155], v[186:189], v[62:65]
	v_mfma_f32_16x16x32_bf16 v[58:61], v[160:163], v[186:189], v[58:61]
	v_mfma_f32_16x16x32_bf16 v[46:49], v[166:169], v[182:185], v[46:49]
	v_mfma_f32_16x16x32_bf16 v[42:45], v[174:177], v[182:185], v[42:45]
	v_mfma_f32_16x16x32_bf16 v[46:49], v[170:173], v[186:189], v[46:49]
	v_mfma_f32_16x16x32_bf16 v[42:45], v[178:181], v[186:189], v[42:45]
	v_mfma_f32_16x16x32_bf16 v[54:57], v[148:151], v[190:193], v[54:57]
	v_mfma_f32_16x16x32_bf16 v[50:53], v[156:159], v[190:193], v[50:53]
	v_mfma_f32_16x16x32_bf16 v[54:57], v[152:155], v[194:197], v[54:57]
	v_mfma_f32_16x16x32_bf16 v[50:53], v[160:163], v[194:197], v[50:53]
	v_mfma_f32_16x16x32_bf16 v[30:33], v[166:169], v[190:193], v[30:33]
	v_mfma_f32_16x16x32_bf16 v[26:29], v[174:177], v[190:193], v[26:29]
	v_mfma_f32_16x16x32_bf16 v[30:33], v[170:173], v[194:197], v[30:33]
	v_mfma_f32_16x16x32_bf16 v[26:29], v[178:181], v[194:197], v[26:29]
	s_cmp_eq_u32 s12, 0
	s_cbranch_scc1 .Lp7_sk3
	v_mfma_f32_16x16x32_bf16 v[38:41], v[148:151], v[198:201], v[38:41]
	v_mfma_f32_16x16x32_bf16 v[34:37], v[156:159], v[198:201], v[34:37]
	v_mfma_f32_16x16x32_bf16 v[38:41], v[152:155], v[202:205], v[38:41]
	v_mfma_f32_16x16x32_bf16 v[34:37], v[160:163], v[202:205], v[34:37]
	v_mfma_f32_16x16x32_bf16 v[14:17], v[166:169], v[198:201], v[14:17]
	v_mfma_f32_16x16x32_bf16 v[10:13], v[174:177], v[198:201], v[10:13]
	v_mfma_f32_16x16x32_bf16 v[14:17], v[170:173], v[202:205], v[14:17]
	v_mfma_f32_16x16x32_bf16 v[10:13], v[178:181], v[202:205], v[10:13]
.Lp7_sk3:
	s_barrier
	s_add_i32 s78, s78, 2
	s_add_u32 s50, s50, 0x100
	s_addc_u32 s51, s51, 0
	s_add_u32 s76, s76, 0x100
	s_addc_u32 s77, s77, 0
	s_cmp_gt_u32 s78, 13
	s_cbranch_scc0 .Lp7_loopB
	s_branch .Lp7_loopX
.Lp7_loopA:
	ds_read_b128 v[148:151], v144
	ds_read_b128 v[152:155], v144 offset:1024
	ds_read_b128 v[156:159], v144 offset:2048
	ds_read_b128 v[160:163], v144 offset:3072
	ds_read_b128 v[166:169], v145
	ds_read_b128 v[170:173], v145 offset:1024
	ds_read_b128 v[174:177], v145 offset:2048
	ds_read_b128 v[178:181], v145 offset:3072
	s_add_u32 s52, s50, 0xfffd8080
	s_addc_u32 s53, s51, -1
	s_cmp_eq_u32 s78, 12
	s_cselect_b32 s55, s45, s53
	s_cselect_b32 s54, s74, s52
	s_cselect_b32 s53, s23, s77
	s_cselect_b32 s52, s75, s76
	v_lshl_add_u64 v[214:215], s[50:51], 0, v[134:135]
	ds_read_b128 v[182:185], v146
	ds_read_b128 v[186:189], v146 offset:1024
	ds_read_b128 v[190:193], v146 offset:2048
	ds_read_b128 v[194:197], v146 offset:3072
	ds_read_b128 v[198:201], v146 offset:4096
	ds_read_b128 v[202:205], v146 offset:5120
	v_lshl_add_u64 v[214:215], s[50:51], 0, v[136:137]
	s_add_i32 m0, s25, 0xe000
	s_nop 0
	global_load_lds_dwordx4 v[214:215], off
	s_waitcnt vmcnt(6)
	s_waitcnt lgkmcnt(0)
	s_barrier
	s_waitcnt lgkmcnt(0)
	v_mfma_f32_16x16x32_bf16 v[126:129], v[148:151], v[182:185], v[126:129]
	v_mfma_f32_16x16x32_bf16 v[122:125], v[156:159], v[182:185], v[122:125]
	v_mfma_f32_16x16x32_bf16 v[126:129], v[152:155], v[186:189], v[126:129]
	v_mfma_f32_16x16x32_bf16 v[122:125], v[160:163], v[186:189], v[122:125]
	v_mfma_f32_16x16x32_bf16 v[110:113], v[166:169], v[182:185], v[110:113]
	v_mfma_f32_16x16x32_bf16 v[106:109], v[174:177], v[182:185], v[106:109]
	v_mfma_f32_16x16x32_bf16 v[110:113], v[170:173], v[186:189], v[110:113]
	v_mfma_f32_16x16x32_bf16 v[106:109], v[178:181], v[186:189], v[106:109]
	v_mfma_f32_16x16x32_bf16 v[118:121], v[148:151], v[190:193], v[118:121]
	v_mfma_f32_16x16x32_bf16 v[114:117], v[156:159], v[190:193], v[114:117]
	v_mfma_f32_16x16x32_bf16 v[118:121], v[152:155], v[194:197], v[118:121]
	v_mfma_f32_16x16x32_bf16 v[114:117], v[160:163], v[194:197], v[114:117]
	v_mfma_f32_16x16x32_bf16 v[94:97], v[166:169], v[190:193], v[94:97]
	v_mfma_f32_16x16x32_bf16 v[90:93], v[174:177], v[190:193], v[90:93]
	v_mfma_f32_16x16x32_bf16 v[94:97], v[170:173], v[194:197], v[94:97]
	v_mfma_f32_16x16x32_bf16 v[90:93], v[178:181], v[194:197], v[90:93]
	s_cmp_eq_u32 s12, 0
	s_cbranch_scc1 .Lp7_skA0
	v_mfma_f32_16x16x32_bf16 v[102:105], v[148:151], v[198:201], v[102:105]
	v_mfma_f32_16x16x32_bf16 v[98:101], v[156:159], v[198:201], v[98:101]
	v_mfma_f32_16x16x32_bf16 v[102:105], v[152:155], v[202:205], v[102:105]
	v_mfma_f32_16x16x32_bf16 v[98:101], v[160:163], v[202:205], v[98:101]
	v_mfma_f32_16x16x32_bf16 v[78:81], v[166:169], v[198:201], v[78:81]
	v_mfma_f32_16x16x32_bf16 v[74:77], v[174:177], v[198:201], v[74:77]
	v_mfma_f32_16x16x32_bf16 v[78:81], v[170:173], v[202:205], v[78:81]
	v_mfma_f32_16x16x32_bf16 v[74:77], v[178:181], v[202:205], v[74:77]
.Lp7_skA0:
	s_barrier
	s_add_i32 s79, s67, s58
	v_lshl_add_u64 v[214:215], s[52:53], 0, v[130:131]
	s_mov_b32 m0, s79
	ds_read_b128 v[182:185], v146 offset:16384
	ds_read_b128 v[186:189], v146 offset:17408
	ds_read_b128 v[190:193], v146 offset:18432
	ds_read_b128 v[194:197], v146 offset:19456
	ds_read_b128 v[198:201], v146 offset:20480
	ds_read_b128 v[202:205], v146 offset:21504
	global_load_lds_dwordx4 v[214:215], off
	s_add_i32 m0, s79, 0x2000
	s_add_u32 s80, s52, 0x40000
	v_lshl_add_u64 v[216:217], s[52:53], 0, v[132:133]
	s_addc_u32 s81, s53, 0
	s_add_i32 s79, s68, s58
	global_load_lds_dwordx4 v[216:217], off
	v_lshl_add_u64 v[218:219], s[80:81], 0, v[130:131]
	s_mov_b32 m0, s79
	v_lshl_add_u64 v[220:221], s[54:55], 0, v[132:133]
	global_load_lds_dwordx4 v[218:219], off
	v_lshl_add_u64 v[218:219], s[80:81], 0, v[132:133]
	s_add_i32 m0, s79, 0x2000
	s_nop 0
	global_load_lds_dwordx4 v[218:219], off
	v_lshl_add_u64 v[218:219], s[54:55], 0, v[130:131]
	s_nop 0
	s_mov_b32 m0, s60
	s_nop 0
	global_load_lds_dwordx4 v[220:221], off
	s_waitcnt vmcnt(6)
	s_waitcnt lgkmcnt(0)
	s_barrier
	s_waitcnt lgkmcnt(0)
	v_mfma_f32_16x16x32_bf16 v[62:65], v[148:151], v[182:185], v[62:65]
	v_mfma_f32_16x16x32_bf16 v[58:61], v[156:159], v[182:185], v[58:61]
	v_mfma_f32_16x16x32_bf16 v[62:65], v[152:155], v[186:189], v[62:65]
	v_mfma_f32_16x16x32_bf16 v[58:61], v[160:163], v[186:189], v[58:61]
	v_mfma_f32_16x16x32_bf16 v[46:49], v[166:169], v[182:185], v[46:49]
	v_mfma_f32_16x16x32_bf16 v[42:45], v[174:177], v[182:185], v[42:45]
	v_mfma_f32_16x16x32_bf16 v[46:49], v[170:173], v[186:189], v[46:49]
	v_mfma_f32_16x16x32_bf16 v[42:45], v[178:181], v[186:189], v[42:45]
	v_mfma_f32_16x16x32_bf16 v[54:57], v[148:151], v[190:193], v[54:57]
	v_mfma_f32_16x16x32_bf16 v[50:53], v[156:159], v[190:193], v[50:53]
	v_mfma_f32_16x16x32_bf16 v[54:57], v[152:155], v[194:197], v[54:57]
	v_mfma_f32_16x16x32_bf16 v[50:53], v[160:163], v[194:197], v[50:53]
	v_mfma_f32_16x16x32_bf16 v[30:33], v[166:169], v[190:193], v[30:33]
	v_mfma_f32_16x16x32_bf16 v[26:29], v[174:177], v[190:193], v[26:29]
	v_mfma_f32_16x16x32_bf16 v[30:33], v[170:173], v[194:197], v[30:33]
	v_mfma_f32_16x16x32_bf16 v[26:29], v[178:181], v[194:197], v[26:29]
	s_cmp_eq_u32 s12, 0
	s_cbranch_scc1 .Lp7_skA1
	v_mfma_f32_16x16x32_bf16 v[38:41], v[148:151], v[198:201], v[38:41]
	v_mfma_f32_16x16x32_bf16 v[34:37], v[156:159], v[198:201], v[34:37]
	v_mfma_f32_16x16x32_bf16 v[38:41], v[152:155], v[202:205], v[38:41]
	v_mfma_f32_16x16x32_bf16 v[34:37], v[160:163], v[202:205], v[34:37]
	v_mfma_f32_16x16x32_bf16 v[14:17], v[166:169], v[198:201], v[14:17]
	v_mfma_f32_16x16x32_bf16 v[10:13], v[174:177], v[198:201], v[10:13]
	v_mfma_f32_16x16x32_bf16 v[14:17], v[170:173], v[202:205], v[14:17]
	v_mfma_f32_16x16x32_bf16 v[10:13], v[178:181], v[202:205], v[10:13]
.Lp7_skA1:
	s_barrier
	s_add_i32 s79, 0, 0x18000
	v_add_u32_e32 v147, s79, v142
	s_add_i32 s80, 0, 0x1c000
	ds_read_b128 v[148:151], v147
	ds_read_b128 v[152:155], v147 offset:1024
	ds_read_b128 v[156:159], v147 offset:2048
	ds_read_b128 v[160:163], v147 offset:3072
	v_add_u32_e32 v147, s80, v142
	ds_read_b128 v[166:169], v147
	ds_read_b128 v[170:173], v147 offset:1024
	ds_read_b128 v[174:177], v147 offset:2048
	ds_read_b128 v[178:181], v147 offset:3072
	s_add_u32 s54, s54, 0x28000
	s_addc_u32 s55, s55, 0
	v_lshl_add_u64 v[222:223], s[54:55], 0, v[130:131]
	ds_read_b128 v[182:185], v146 offset:32768
	ds_read_b128 v[186:189], v146 offset:33792
	ds_read_b128 v[190:193], v146 offset:34816
	ds_read_b128 v[194:197], v146 offset:35840
	ds_read_b128 v[198:201], v146 offset:36864
	ds_read_b128 v[202:205], v146 offset:37888
	v_lshl_add_u64 v[222:223], s[54:55], 0, v[132:133]
	s_mov_b32 m0, s62
	s_nop 0
	global_load_lds_dwordx4 v[222:223], off
	s_waitcnt vmcnt(6)
	s_waitcnt lgkmcnt(0)
	s_barrier
	s_waitcnt lgkmcnt(0)
	v_mfma_f32_16x16x32_bf16 v[126:129], v[148:151], v[182:185], v[126:129]
	v_mfma_f32_16x16x32_bf16 v[122:125], v[156:159], v[182:185], v[122:125]
	v_mfma_f32_16x16x32_bf16 v[126:129], v[152:155], v[186:189], v[126:129]
	v_mfma_f32_16x16x32_bf16 v[122:125], v[160:163], v[186:189], v[122:125]
	v_mfma_f32_16x16x32_bf16 v[110:113], v[166:169], v[182:185], v[110:113]
	v_mfma_f32_16x16x32_bf16 v[106:109], v[174:177], v[182:185], v[106:109]
	v_mfma_f32_16x16x32_bf16 v[110:113], v[170:173], v[186:189], v[110:113]
	v_mfma_f32_16x16x32_bf16 v[106:109], v[178:181], v[186:189], v[106:109]
	v_mfma_f32_16x16x32_bf16 v[118:121], v[148:151], v[190:193], v[118:121]
	v_mfma_f32_16x16x32_bf16 v[114:117], v[156:159], v[190:193], v[114:117]
	v_mfma_f32_16x16x32_bf16 v[118:121], v[152:155], v[194:197], v[118:121]
	v_mfma_f32_16x16x32_bf16 v[114:117], v[160:163], v[194:197], v[114:117]
	v_mfma_f32_16x16x32_bf16 v[94:97], v[166:169], v[190:193], v[94:97]
	v_mfma_f32_16x16x32_bf16 v[90:93], v[174:177], v[190:193], v[90:93]
	v_mfma_f32_16x16x32_bf16 v[94:97], v[170:173], v[194:197], v[94:97]
	v_mfma_f32_16x16x32_bf16 v[90:93], v[178:181], v[194:197], v[90:93]
	s_cmp_eq_u32 s12, 0
	s_cbranch_scc1 .Lp7_skA2
	v_mfma_f32_16x16x32_bf16 v[102:105], v[148:151], v[198:201], v[102:105]
	v_mfma_f32_16x16x32_bf16 v[98:101], v[156:159], v[198:201], v[98:101]
	v_mfma_f32_16x16x32_bf16 v[102:105], v[152:155], v[202:205], v[102:105]
	v_mfma_f32_16x16x32_bf16 v[98:101], v[160:163], v[202:205], v[98:101]
	v_mfma_f32_16x16x32_bf16 v[78:81], v[166:169], v[198:201], v[78:81]
	v_mfma_f32_16x16x32_bf16 v[74:77], v[174:177], v[198:201], v[74:77]
	v_mfma_f32_16x16x32_bf16 v[78:81], v[170:173], v[202:205], v[78:81]
	v_mfma_f32_16x16x32_bf16 v[74:77], v[178:181], v[202:205], v[74:77]
.Lp7_skA2:
	s_barrier
	s_add_i32 s54, s79, s58
	v_lshl_add_u64 v[214:215], v[214:215], 0, s[10:11]
	s_mov_b32 m0, s54
	ds_read_b128 v[182:185], v146 offset:49152
	ds_read_b128 v[186:189], v146 offset:50176
	ds_read_b128 v[190:193], v146 offset:51200
	ds_read_b128 v[194:197], v146 offset:52224
	ds_read_b128 v[198:201], v146 offset:53248
	ds_read_b128 v[202:205], v146 offset:54272
	global_load_lds_dwordx4 v[214:215], off
	s_add_i32 m0, s54, 0x2000
	s_add_u32 s52, s52, 0x40080
	v_lshl_add_u64 v[214:215], v[216:217], 0, s[10:11]
	s_addc_u32 s53, s53, 0
	s_add_i32 s54, s80, s58
	global_load_lds_dwordx4 v[214:215], off
	v_lshl_add_u64 v[214:215], s[52:53], 0, v[130:131]
	s_mov_b32 m0, s54
	s_nop 0
	global_load_lds_dwordx4 v[214:215], off
	v_lshl_add_u64 v[214:215], s[52:53], 0, v[132:133]
	s_add_i32 m0, s54, 0x2000
	s_nop 0
	global_load_lds_dwordx4 v[214:215], off
	v_lshl_add_u64 v[214:215], v[218:219], 0, s[10:11]
	s_nop 0
	v_lshl_add_u64 v[214:215], v[220:221], 0, s[10:11]
	s_mov_b32 m0, s66
	s_nop 0
	global_load_lds_dwordx4 v[214:215], off
	s_waitcnt vmcnt(6)
	s_waitcnt lgkmcnt(0)
	s_barrier
	s_waitcnt lgkmcnt(0)
	v_mfma_f32_16x16x32_bf16 v[62:65], v[148:151], v[182:185], v[62:65]
	v_mfma_f32_16x16x32_bf16 v[58:61], v[156:159], v[182:185], v[58:61]
	v_mfma_f32_16x16x32_bf16 v[62:65], v[152:155], v[186:189], v[62:65]
	v_mfma_f32_16x16x32_bf16 v[58:61], v[160:163], v[186:189], v[58:61]
	v_mfma_f32_16x16x32_bf16 v[46:49], v[166:169], v[182:185], v[46:49]
	v_mfma_f32_16x16x32_bf16 v[42:45], v[174:177], v[182:185], v[42:45]
	v_mfma_f32_16x16x32_bf16 v[46:49], v[170:173], v[186:189], v[46:49]
	v_mfma_f32_16x16x32_bf16 v[42:45], v[178:181], v[186:189], v[42:45]
	v_mfma_f32_16x16x32_bf16 v[54:57], v[148:151], v[190:193], v[54:57]
	v_mfma_f32_16x16x32_bf16 v[50:53], v[156:159], v[190:193], v[50:53]
	v_mfma_f32_16x16x32_bf16 v[54:57], v[152:155], v[194:197], v[54:57]
	v_mfma_f32_16x16x32_bf16 v[50:53], v[160:163], v[194:197], v[50:53]
	v_mfma_f32_16x16x32_bf16 v[30:33], v[166:169], v[190:193], v[30:33]
	v_mfma_f32_16x16x32_bf16 v[26:29], v[174:177], v[190:193], v[26:29]
	v_mfma_f32_16x16x32_bf16 v[30:33], v[170:173], v[194:197], v[30:33]
	v_mfma_f32_16x16x32_bf16 v[26:29], v[178:181], v[194:197], v[26:29]
	s_cmp_eq_u32 s12, 0
	s_cbranch_scc1 .Lp7_skA3
	v_mfma_f32_16x16x32_bf16 v[38:41], v[148:151], v[198:201], v[38:41]
	v_mfma_f32_16x16x32_bf16 v[34:37], v[156:159], v[198:201], v[34:37]
	v_mfma_f32_16x16x32_bf16 v[38:41], v[152:155], v[202:205], v[38:41]
	v_mfma_f32_16x16x32_bf16 v[34:37], v[160:163], v[202:205], v[34:37]
	v_mfma_f32_16x16x32_bf16 v[14:17], v[166:169], v[198:201], v[14:17]
	v_mfma_f32_16x16x32_bf16 v[10:13], v[174:177], v[198:201], v[10:13]
	v_mfma_f32_16x16x32_bf16 v[14:17], v[170:173], v[202:205], v[14:17]
	v_mfma_f32_16x16x32_bf16 v[10:13], v[178:181], v[202:205], v[10:13]
.Lp7_skA3:
	s_barrier
	s_add_i32 s78, s78, 2
	s_add_u32 s50, s50, 0x100
	s_addc_u32 s51, s51, 0
	s_add_u32 s76, s76, 0x100
	s_addc_u32 s77, s77, 0
	s_cmp_gt_u32 s78, 13
	s_cbranch_scc0 .Lp7_loopA

.Lp10_loopB:
	ds_read_b128 v[146:149], v143
	ds_read_b128 v[150:153], v143 offset:1024
	ds_read_b128 v[154:157], v143 offset:2048
	ds_read_b128 v[158:161], v143 offset:3072
	ds_read_b128 v[166:169], v144
	ds_read_b128 v[170:173], v144 offset:1024
	ds_read_b128 v[174:177], v144 offset:2048
	ds_read_b128 v[178:181], v144 offset:3072
	s_add_u32 s44, s36, 0xfff92080
	s_addc_u32 s45, s37, -1
	s_cmp_eq_u32 s70, 40
	s_cselect_b32 s47, s1, s45
	s_cselect_b32 s46, s0, s44
	s_cselect_b32 s45, s25, s69
	s_cselect_b32 s44, s24, s68
	v_lshl_add_u64 v[162:163], s[36:37], 0, v[132:133]
	s_add_i32 m0, s50, 0xc000
	ds_read_b128 v[182:185], v145
	ds_read_b128 v[186:189], v145 offset:1024
	ds_read_b128 v[190:193], v145 offset:2048
	ds_read_b128 v[194:197], v145 offset:3072
	ds_read_b128 v[198:201], v145 offset:4096
	ds_read_b128 v[202:205], v145 offset:5120
	global_load_lds_dwordx4 v[162:163], off
	v_lshl_add_u64 v[162:163], s[36:37], 0, v[134:135]
	s_add_i32 m0, s50, 0xe000
	s_nop 0
	global_load_lds_dwordx4 v[162:163], off
	s_waitcnt vmcnt(8)
	s_waitcnt lgkmcnt(0)
	s_barrier
	s_waitcnt lgkmcnt(0)
	v_mfma_f32_16x16x32_bf16 v[124:127], v[146:149], v[182:185], v[124:127]
	v_mfma_f32_16x16x32_bf16 v[120:123], v[154:157], v[182:185], v[120:123]
	v_mfma_f32_16x16x32_bf16 v[124:127], v[150:153], v[186:189], v[124:127]
	v_mfma_f32_16x16x32_bf16 v[120:123], v[158:161], v[186:189], v[120:123]
	v_mfma_f32_16x16x32_bf16 v[108:111], v[166:169], v[182:185], v[108:111]
	v_mfma_f32_16x16x32_bf16 v[104:107], v[174:177], v[182:185], v[104:107]
	v_mfma_f32_16x16x32_bf16 v[108:111], v[170:173], v[186:189], v[108:111]
	v_mfma_f32_16x16x32_bf16 v[104:107], v[178:181], v[186:189], v[104:107]
	v_mfma_f32_16x16x32_bf16 v[116:119], v[146:149], v[190:193], v[116:119]
	v_mfma_f32_16x16x32_bf16 v[112:115], v[154:157], v[190:193], v[112:115]
	v_mfma_f32_16x16x32_bf16 v[116:119], v[150:153], v[194:197], v[116:119]
	v_mfma_f32_16x16x32_bf16 v[112:115], v[158:161], v[194:197], v[112:115]
	v_mfma_f32_16x16x32_bf16 v[92:95], v[166:169], v[190:193], v[92:95]
	v_mfma_f32_16x16x32_bf16 v[88:91], v[174:177], v[190:193], v[88:91]
	v_mfma_f32_16x16x32_bf16 v[92:95], v[170:173], v[194:197], v[92:95]
	v_mfma_f32_16x16x32_bf16 v[88:91], v[178:181], v[194:197], v[88:91]
	s_cmp_eq_u32 s12, 0
	s_cbranch_scc1 .Lp10_sk0
	v_mfma_f32_16x16x32_bf16 v[100:103], v[146:149], v[198:201], v[100:103]
	v_mfma_f32_16x16x32_bf16 v[96:99], v[154:157], v[198:201], v[96:99]
	v_mfma_f32_16x16x32_bf16 v[100:103], v[150:153], v[202:205], v[100:103]
	v_mfma_f32_16x16x32_bf16 v[96:99], v[158:161], v[202:205], v[96:99]
	v_mfma_f32_16x16x32_bf16 v[76:79], v[166:169], v[198:201], v[76:79]
	v_mfma_f32_16x16x32_bf16 v[72:75], v[174:177], v[198:201], v[72:75]
	v_mfma_f32_16x16x32_bf16 v[76:79], v[170:173], v[202:205], v[76:79]
	v_mfma_f32_16x16x32_bf16 v[72:75], v[178:181], v[202:205], v[72:75]
.Lp10_sk0:
	s_barrier
	s_add_i32 s71, s58, s48
	v_lshl_add_u64 v[162:163], s[44:45], 0, v[128:129]
	s_mov_b32 m0, s71
	ds_read_b128 v[182:185], v145 offset:16384
	ds_read_b128 v[186:189], v145 offset:17408
	ds_read_b128 v[190:193], v145 offset:18432
	ds_read_b128 v[194:197], v145 offset:19456
	ds_read_b128 v[198:201], v145 offset:20480
	ds_read_b128 v[202:205], v145 offset:21504
	global_load_lds_dwordx4 v[162:163], off
	s_add_i32 m0, s71, 0x2000
	s_add_u32 s72, s44, 0xb0000
	v_lshl_add_u64 v[214:215], s[44:45], 0, v[130:131]
	s_addc_u32 s73, s45, 0
	s_add_i32 s71, s59, s48
	global_load_lds_dwordx4 v[214:215], off
	v_lshl_add_u64 v[216:217], s[72:73], 0, v[128:129]
	s_mov_b32 m0, s71
	v_lshl_add_u64 v[218:219], s[46:47], 0, v[130:131]
	global_load_lds_dwordx4 v[216:217], off
	v_lshl_add_u64 v[216:217], s[72:73], 0, v[130:131]
	s_add_i32 m0, s71, 0x2000
	s_nop 0
	global_load_lds_dwordx4 v[216:217], off
	v_lshl_add_u64 v[216:217], s[46:47], 0, v[128:129]
	s_mov_b32 m0, s50
	s_nop 0
	global_load_lds_dwordx4 v[216:217], off
	s_mov_b32 m0, s51
	s_nop 0
	global_load_lds_dwordx4 v[218:219], off
	s_waitcnt vmcnt(8)
	s_waitcnt lgkmcnt(0)
	s_barrier
	s_waitcnt lgkmcnt(0)
	v_mfma_f32_16x16x32_bf16 v[60:63], v[146:149], v[182:185], v[60:63]
	v_mfma_f32_16x16x32_bf16 v[56:59], v[154:157], v[182:185], v[56:59]
	v_mfma_f32_16x16x32_bf16 v[60:63], v[150:153], v[186:189], v[60:63]
	v_mfma_f32_16x16x32_bf16 v[56:59], v[158:161], v[186:189], v[56:59]
	v_mfma_f32_16x16x32_bf16 v[44:47], v[166:169], v[182:185], v[44:47]
	v_mfma_f32_16x16x32_bf16 v[40:43], v[174:177], v[182:185], v[40:43]
	v_mfma_f32_16x16x32_bf16 v[44:47], v[170:173], v[186:189], v[44:47]
	v_mfma_f32_16x16x32_bf16 v[40:43], v[178:181], v[186:189], v[40:43]
	v_mfma_f32_16x16x32_bf16 v[52:55], v[146:149], v[190:193], v[52:55]
	v_mfma_f32_16x16x32_bf16 v[48:51], v[154:157], v[190:193], v[48:51]
	v_mfma_f32_16x16x32_bf16 v[52:55], v[150:153], v[194:197], v[52:55]
	v_mfma_f32_16x16x32_bf16 v[48:51], v[158:161], v[194:197], v[48:51]
	v_mfma_f32_16x16x32_bf16 v[28:31], v[166:169], v[190:193], v[28:31]
	v_mfma_f32_16x16x32_bf16 v[24:27], v[174:177], v[190:193], v[24:27]
	v_mfma_f32_16x16x32_bf16 v[28:31], v[170:173], v[194:197], v[28:31]
	v_mfma_f32_16x16x32_bf16 v[24:27], v[178:181], v[194:197], v[24:27]
	s_cmp_eq_u32 s12, 0
	s_cbranch_scc1 .Lp10_sk1
	v_mfma_f32_16x16x32_bf16 v[36:39], v[146:149], v[198:201], v[36:39]
	v_mfma_f32_16x16x32_bf16 v[32:35], v[154:157], v[198:201], v[32:35]
	v_mfma_f32_16x16x32_bf16 v[36:39], v[150:153], v[202:205], v[36:39]
	v_mfma_f32_16x16x32_bf16 v[32:35], v[158:161], v[202:205], v[32:35]
	v_mfma_f32_16x16x32_bf16 v[12:15], v[166:169], v[198:201], v[12:15]
	v_mfma_f32_16x16x32_bf16 v[8:11], v[174:177], v[198:201], v[8:11]
	v_mfma_f32_16x16x32_bf16 v[12:15], v[170:173], v[202:205], v[12:15]
	v_mfma_f32_16x16x32_bf16 v[8:11], v[178:181], v[202:205], v[8:11]
.Lp10_sk1:
	s_barrier
	s_add_i32 s71, 0, 0x18000
	s_add_i32 s72, 0, 0x1c000
	v_add_u32_e32 v158, s71, v141
	v_add_u32_e32 v165, s72, v141
	ds_read_b128 v[146:149], v158
	ds_read_b128 v[150:153], v158 offset:1024
	ds_read_b128 v[154:157], v158 offset:2048
	ds_read_b128 v[158:161], v158 offset:3072
	ds_read_b128 v[166:169], v165
	ds_read_b128 v[170:173], v165 offset:1024
	ds_read_b128 v[174:177], v165 offset:2048
	ds_read_b128 v[178:181], v165 offset:3072
	s_add_u32 s46, s46, 0x6e000
	s_addc_u32 s47, s47, 0
	s_mov_b32 m0, s52
	v_lshl_add_u64 v[220:221], s[46:47], 0, v[128:129]
	ds_read_b128 v[182:185], v145 offset:32768
	ds_read_b128 v[186:189], v145 offset:33792
	ds_read_b128 v[190:193], v145 offset:34816
	ds_read_b128 v[194:197], v145 offset:35840
	ds_read_b128 v[198:201], v145 offset:36864
	ds_read_b128 v[202:205], v145 offset:37888
	global_load_lds_dwordx4 v[220:221], off
	v_lshl_add_u64 v[220:221], s[46:47], 0, v[130:131]
	s_mov_b32 m0, s53
	s_nop 0
	global_load_lds_dwordx4 v[220:221], off
	s_waitcnt vmcnt(8)
	s_waitcnt lgkmcnt(0)
	s_barrier
	s_waitcnt lgkmcnt(0)
	v_mfma_f32_16x16x32_bf16 v[124:127], v[146:149], v[182:185], v[124:127]
	v_mfma_f32_16x16x32_bf16 v[120:123], v[154:157], v[182:185], v[120:123]
	v_mfma_f32_16x16x32_bf16 v[124:127], v[150:153], v[186:189], v[124:127]
	v_mfma_f32_16x16x32_bf16 v[120:123], v[158:161], v[186:189], v[120:123]
	v_mfma_f32_16x16x32_bf16 v[108:111], v[166:169], v[182:185], v[108:111]
	v_mfma_f32_16x16x32_bf16 v[104:107], v[174:177], v[182:185], v[104:107]
	v_mfma_f32_16x16x32_bf16 v[108:111], v[170:173], v[186:189], v[108:111]
	v_mfma_f32_16x16x32_bf16 v[104:107], v[178:181], v[186:189], v[104:107]
	v_mfma_f32_16x16x32_bf16 v[116:119], v[146:149], v[190:193], v[116:119]
	v_mfma_f32_16x16x32_bf16 v[112:115], v[154:157], v[190:193], v[112:115]
	v_mfma_f32_16x16x32_bf16 v[116:119], v[150:153], v[194:197], v[116:119]
	v_mfma_f32_16x16x32_bf16 v[112:115], v[158:161], v[194:197], v[112:115]
	v_mfma_f32_16x16x32_bf16 v[92:95], v[166:169], v[190:193], v[92:95]
	v_mfma_f32_16x16x32_bf16 v[88:91], v[174:177], v[190:193], v[88:91]
	v_mfma_f32_16x16x32_bf16 v[92:95], v[170:173], v[194:197], v[92:95]
	v_mfma_f32_16x16x32_bf16 v[88:91], v[178:181], v[194:197], v[88:91]
	s_cmp_eq_u32 s12, 0
	s_cbranch_scc1 .Lp10_sk2
	v_mfma_f32_16x16x32_bf16 v[100:103], v[146:149], v[198:201], v[100:103]
	v_mfma_f32_16x16x32_bf16 v[96:99], v[154:157], v[198:201], v[96:99]
	v_mfma_f32_16x16x32_bf16 v[100:103], v[150:153], v[202:205], v[100:103]
	v_mfma_f32_16x16x32_bf16 v[96:99], v[158:161], v[202:205], v[96:99]
	v_mfma_f32_16x16x32_bf16 v[76:79], v[166:169], v[198:201], v[76:79]
	v_mfma_f32_16x16x32_bf16 v[72:75], v[174:177], v[198:201], v[72:75]
	v_mfma_f32_16x16x32_bf16 v[76:79], v[170:173], v[202:205], v[76:79]
	v_mfma_f32_16x16x32_bf16 v[72:75], v[178:181], v[202:205], v[72:75]
.Lp10_sk2:
	s_barrier
	s_add_i32 s46, s71, s48
	v_lshl_add_u64 v[162:163], v[162:163], 0, s[10:11]
	s_mov_b32 m0, s46
	ds_read_b128 v[182:185], v145 offset:49152
	ds_read_b128 v[186:189], v145 offset:50176
	ds_read_b128 v[190:193], v145 offset:51200
	ds_read_b128 v[194:197], v145 offset:52224
	ds_read_b128 v[198:201], v145 offset:53248
	ds_read_b128 v[202:205], v145 offset:54272
	global_load_lds_dwordx4 v[162:163], off
	s_add_i32 m0, s46, 0x2000
	s_add_u32 s44, s44, 0xb0080
	v_lshl_add_u64 v[162:163], v[214:215], 0, s[10:11]
	s_addc_u32 s45, s45, 0
	s_add_i32 s46, s72, s48
	global_load_lds_dwordx4 v[162:163], off
	v_lshl_add_u64 v[162:163], s[44:45], 0, v[128:129]
	s_mov_b32 m0, s46
	s_nop 0
	global_load_lds_dwordx4 v[162:163], off
	v_lshl_add_u64 v[162:163], s[44:45], 0, v[130:131]
	s_add_i32 m0, s46, 0x2000
	s_nop 0
	global_load_lds_dwordx4 v[162:163], off
	v_lshl_add_u64 v[162:163], v[216:217], 0, s[10:11]
	s_mov_b32 m0, s56
	s_nop 0
	global_load_lds_dwordx4 v[162:163], off
	v_lshl_add_u64 v[162:163], v[218:219], 0, s[10:11]
	s_mov_b32 m0, s57
	s_nop 0
	global_load_lds_dwordx4 v[162:163], off
	s_waitcnt vmcnt(8)
	s_waitcnt lgkmcnt(0)
	s_barrier
	s_waitcnt lgkmcnt(0)
	v_mfma_f32_16x16x32_bf16 v[60:63], v[146:149], v[182:185], v[60:63]
	v_mfma_f32_16x16x32_bf16 v[56:59], v[154:157], v[182:185], v[56:59]
	v_mfma_f32_16x16x32_bf16 v[60:63], v[150:153], v[186:189], v[60:63]
	v_mfma_f32_16x16x32_bf16 v[56:59], v[158:161], v[186:189], v[56:59]
	v_mfma_f32_16x16x32_bf16 v[44:47], v[166:169], v[182:185], v[44:47]
	v_mfma_f32_16x16x32_bf16 v[40:43], v[174:177], v[182:185], v[40:43]
	v_mfma_f32_16x16x32_bf16 v[44:47], v[170:173], v[186:189], v[44:47]
	v_mfma_f32_16x16x32_bf16 v[40:43], v[178:181], v[186:189], v[40:43]
	v_mfma_f32_16x16x32_bf16 v[52:55], v[146:149], v[190:193], v[52:55]
	v_mfma_f32_16x16x32_bf16 v[48:51], v[154:157], v[190:193], v[48:51]
	v_mfma_f32_16x16x32_bf16 v[52:55], v[150:153], v[194:197], v[52:55]
	v_mfma_f32_16x16x32_bf16 v[48:51], v[158:161], v[194:197], v[48:51]
	v_mfma_f32_16x16x32_bf16 v[28:31], v[166:169], v[190:193], v[28:31]
	v_mfma_f32_16x16x32_bf16 v[24:27], v[174:177], v[190:193], v[24:27]
	v_mfma_f32_16x16x32_bf16 v[28:31], v[170:173], v[194:197], v[28:31]
	v_mfma_f32_16x16x32_bf16 v[24:27], v[178:181], v[194:197], v[24:27]
	s_cmp_eq_u32 s12, 0
	s_cbranch_scc1 .Lp10_sk3
	v_mfma_f32_16x16x32_bf16 v[36:39], v[146:149], v[198:201], v[36:39]
	v_mfma_f32_16x16x32_bf16 v[32:35], v[154:157], v[198:201], v[32:35]
	v_mfma_f32_16x16x32_bf16 v[36:39], v[150:153], v[202:205], v[36:39]
	v_mfma_f32_16x16x32_bf16 v[32:35], v[158:161], v[202:205], v[32:35]
	v_mfma_f32_16x16x32_bf16 v[12:15], v[166:169], v[198:201], v[12:15]
	v_mfma_f32_16x16x32_bf16 v[8:11], v[174:177], v[198:201], v[8:11]
	v_mfma_f32_16x16x32_bf16 v[12:15], v[170:173], v[202:205], v[12:15]
	v_mfma_f32_16x16x32_bf16 v[8:11], v[178:181], v[202:205], v[8:11]
.Lp10_sk3:
	s_barrier
	s_add_i32 s70, s70, 2
	s_add_u32 s36, s36, 0x100
	s_addc_u32 s37, s37, 0
	s_add_u32 s68, s68, 0x100
	s_addc_u32 s69, s69, 0
	s_cmp_gt_u32 s70, 41
	s_cbranch_scc0 .Lp10_loopB
	s_branch .Lp10_loopX
.Lp10_loopA:
	ds_read_b128 v[146:149], v143
	ds_read_b128 v[150:153], v143 offset:1024
	ds_read_b128 v[154:157], v143 offset:2048
	ds_read_b128 v[158:161], v143 offset:3072
	ds_read_b128 v[166:169], v144
	ds_read_b128 v[170:173], v144 offset:1024
	ds_read_b128 v[174:177], v144 offset:2048
	ds_read_b128 v[178:181], v144 offset:3072
	s_add_u32 s44, s36, 0xfff92080
	s_addc_u32 s45, s37, -1
	s_cmp_eq_u32 s70, 40
	s_cselect_b32 s47, s1, s45
	s_cselect_b32 s46, s0, s44
	s_cselect_b32 s45, s25, s69
	s_cselect_b32 s44, s24, s68
	v_lshl_add_u64 v[162:163], s[36:37], 0, v[132:133]
	ds_read_b128 v[182:185], v145
	ds_read_b128 v[186:189], v145 offset:1024
	ds_read_b128 v[190:193], v145 offset:2048
	ds_read_b128 v[194:197], v145 offset:3072
	ds_read_b128 v[198:201], v145 offset:4096
	ds_read_b128 v[202:205], v145 offset:5120
	v_lshl_add_u64 v[162:163], s[36:37], 0, v[134:135]
	s_add_i32 m0, s50, 0xe000
	s_nop 0
	global_load_lds_dwordx4 v[162:163], off
	s_waitcnt vmcnt(6)
	s_waitcnt lgkmcnt(0)
	s_barrier
	s_waitcnt lgkmcnt(0)
	v_mfma_f32_16x16x32_bf16 v[124:127], v[146:149], v[182:185], v[124:127]
	v_mfma_f32_16x16x32_bf16 v[120:123], v[154:157], v[182:185], v[120:123]
	v_mfma_f32_16x16x32_bf16 v[124:127], v[150:153], v[186:189], v[124:127]
	v_mfma_f32_16x16x32_bf16 v[120:123], v[158:161], v[186:189], v[120:123]
	v_mfma_f32_16x16x32_bf16 v[108:111], v[166:169], v[182:185], v[108:111]
	v_mfma_f32_16x16x32_bf16 v[104:107], v[174:177], v[182:185], v[104:107]
	v_mfma_f32_16x16x32_bf16 v[108:111], v[170:173], v[186:189], v[108:111]
	v_mfma_f32_16x16x32_bf16 v[104:107], v[178:181], v[186:189], v[104:107]
	v_mfma_f32_16x16x32_bf16 v[116:119], v[146:149], v[190:193], v[116:119]
	v_mfma_f32_16x16x32_bf16 v[112:115], v[154:157], v[190:193], v[112:115]
	v_mfma_f32_16x16x32_bf16 v[116:119], v[150:153], v[194:197], v[116:119]
	v_mfma_f32_16x16x32_bf16 v[112:115], v[158:161], v[194:197], v[112:115]
	v_mfma_f32_16x16x32_bf16 v[92:95], v[166:169], v[190:193], v[92:95]
	v_mfma_f32_16x16x32_bf16 v[88:91], v[174:177], v[190:193], v[88:91]
	v_mfma_f32_16x16x32_bf16 v[92:95], v[170:173], v[194:197], v[92:95]
	v_mfma_f32_16x16x32_bf16 v[88:91], v[178:181], v[194:197], v[88:91]
	s_cmp_eq_u32 s12, 0
	s_cbranch_scc1 .Lp10_skA0
	v_mfma_f32_16x16x32_bf16 v[100:103], v[146:149], v[198:201], v[100:103]
	v_mfma_f32_16x16x32_bf16 v[96:99], v[154:157], v[198:201], v[96:99]
	v_mfma_f32_16x16x32_bf16 v[100:103], v[150:153], v[202:205], v[100:103]
	v_mfma_f32_16x16x32_bf16 v[96:99], v[158:161], v[202:205], v[96:99]
	v_mfma_f32_16x16x32_bf16 v[76:79], v[166:169], v[198:201], v[76:79]
	v_mfma_f32_16x16x32_bf16 v[72:75], v[174:177], v[198:201], v[72:75]
	v_mfma_f32_16x16x32_bf16 v[76:79], v[170:173], v[202:205], v[76:79]
	v_mfma_f32_16x16x32_bf16 v[72:75], v[178:181], v[202:205], v[72:75]
.Lp10_skA0:
	s_barrier
	s_add_i32 s71, s58, s48
	v_lshl_add_u64 v[162:163], s[44:45], 0, v[128:129]
	s_mov_b32 m0, s71
	ds_read_b128 v[182:185], v145 offset:16384
	ds_read_b128 v[186:189], v145 offset:17408
	ds_read_b128 v[190:193], v145 offset:18432
	ds_read_b128 v[194:197], v145 offset:19456
	ds_read_b128 v[198:201], v145 offset:20480
	ds_read_b128 v[202:205], v145 offset:21504
	global_load_lds_dwordx4 v[162:163], off
	s_add_i32 m0, s71, 0x2000
	s_add_u32 s72, s44, 0xb0000
	v_lshl_add_u64 v[214:215], s[44:45], 0, v[130:131]
	s_addc_u32 s73, s45, 0
	s_add_i32 s71, s59, s48
	global_load_lds_dwordx4 v[214:215], off
	v_lshl_add_u64 v[216:217], s[72:73], 0, v[128:129]
	s_mov_b32 m0, s71
	v_lshl_add_u64 v[218:219], s[46:47], 0, v[130:131]
	global_load_lds_dwordx4 v[216:217], off
	v_lshl_add_u64 v[216:217], s[72:73], 0, v[130:131]
	s_add_i32 m0, s71, 0x2000
	s_nop 0
	global_load_lds_dwordx4 v[216:217], off
	v_lshl_add_u64 v[216:217], s[46:47], 0, v[128:129]
	s_nop 0
	s_mov_b32 m0, s51
	s_nop 0
	global_load_lds_dwordx4 v[218:219], off
	s_waitcnt vmcnt(6)
	s_waitcnt lgkmcnt(0)
	s_barrier
	s_waitcnt lgkmcnt(0)
	v_mfma_f32_16x16x32_bf16 v[60:63], v[146:149], v[182:185], v[60:63]
	v_mfma_f32_16x16x32_bf16 v[56:59], v[154:157], v[182:185], v[56:59]
	v_mfma_f32_16x16x32_bf16 v[60:63], v[150:153], v[186:189], v[60:63]
	v_mfma_f32_16x16x32_bf16 v[56:59], v[158:161], v[186:189], v[56:59]
	v_mfma_f32_16x16x32_bf16 v[44:47], v[166:169], v[182:185], v[44:47]
	v_mfma_f32_16x16x32_bf16 v[40:43], v[174:177], v[182:185], v[40:43]
	v_mfma_f32_16x16x32_bf16 v[44:47], v[170:173], v[186:189], v[44:47]
	v_mfma_f32_16x16x32_bf16 v[40:43], v[178:181], v[186:189], v[40:43]
	v_mfma_f32_16x16x32_bf16 v[52:55], v[146:149], v[190:193], v[52:55]
	v_mfma_f32_16x16x32_bf16 v[48:51], v[154:157], v[190:193], v[48:51]
	v_mfma_f32_16x16x32_bf16 v[52:55], v[150:153], v[194:197], v[52:55]
	v_mfma_f32_16x16x32_bf16 v[48:51], v[158:161], v[194:197], v[48:51]
	v_mfma_f32_16x16x32_bf16 v[28:31], v[166:169], v[190:193], v[28:31]
	v_mfma_f32_16x16x32_bf16 v[24:27], v[174:177], v[190:193], v[24:27]
	v_mfma_f32_16x16x32_bf16 v[28:31], v[170:173], v[194:197], v[28:31]
	v_mfma_f32_16x16x32_bf16 v[24:27], v[178:181], v[194:197], v[24:27]
	s_cmp_eq_u32 s12, 0
	s_cbranch_scc1 .Lp10_skA1
	v_mfma_f32_16x16x32_bf16 v[36:39], v[146:149], v[198:201], v[36:39]
	v_mfma_f32_16x16x32_bf16 v[32:35], v[154:157], v[198:201], v[32:35]
	v_mfma_f32_16x16x32_bf16 v[36:39], v[150:153], v[202:205], v[36:39]
	v_mfma_f32_16x16x32_bf16 v[32:35], v[158:161], v[202:205], v[32:35]
	v_mfma_f32_16x16x32_bf16 v[12:15], v[166:169], v[198:201], v[12:15]
	v_mfma_f32_16x16x32_bf16 v[8:11], v[174:177], v[198:201], v[8:11]
	v_mfma_f32_16x16x32_bf16 v[12:15], v[170:173], v[202:205], v[12:15]
	v_mfma_f32_16x16x32_bf16 v[8:11], v[178:181], v[202:205], v[8:11]
.Lp10_skA1:
	s_barrier
	s_add_i32 s71, 0, 0x18000
	s_add_i32 s72, 0, 0x1c000
	v_add_u32_e32 v158, s71, v141
	v_add_u32_e32 v165, s72, v141
	ds_read_b128 v[146:149], v158
	ds_read_b128 v[150:153], v158 offset:1024
	ds_read_b128 v[154:157], v158 offset:2048
	ds_read_b128 v[158:161], v158 offset:3072
	ds_read_b128 v[166:169], v165
	ds_read_b128 v[170:173], v165 offset:1024
	ds_read_b128 v[174:177], v165 offset:2048
	ds_read_b128 v[178:181], v165 offset:3072
	s_add_u32 s46, s46, 0x6e000
	s_addc_u32 s47, s47, 0
	v_lshl_add_u64 v[220:221], s[46:47], 0, v[128:129]
	ds_read_b128 v[182:185], v145 offset:32768
	ds_read_b128 v[186:189], v145 offset:33792
	ds_read_b128 v[190:193], v145 offset:34816
	ds_read_b128 v[194:197], v145 offset:35840
	ds_read_b128 v[198:201], v145 offset:36864
	ds_read_b128 v[202:205], v145 offset:37888
	v_lshl_add_u64 v[220:221], s[46:47], 0, v[130:131]
	s_mov_b32 m0, s53
	s_nop 0
	global_load_lds_dwordx4 v[220:221], off
	s_waitcnt vmcnt(6)
	s_waitcnt lgkmcnt(0)
	s_barrier
	s_waitcnt lgkmcnt(0)
	v_mfma_f32_16x16x32_bf16 v[124:127], v[146:149], v[182:185], v[124:127]
	v_mfma_f32_16x16x32_bf16 v[120:123], v[154:157], v[182:185], v[120:123]
	v_mfma_f32_16x16x32_bf16 v[124:127], v[150:153], v[186:189], v[124:127]
	v_mfma_f32_16x16x32_bf16 v[120:123], v[158:161], v[186:189], v[120:123]
	v_mfma_f32_16x16x32_bf16 v[108:111], v[166:169], v[182:185], v[108:111]
	v_mfma_f32_16x16x32_bf16 v[104:107], v[174:177], v[182:185], v[104:107]
	v_mfma_f32_16x16x32_bf16 v[108:111], v[170:173], v[186:189], v[108:111]
	v_mfma_f32_16x16x32_bf16 v[104:107], v[178:181], v[186:189], v[104:107]
	v_mfma_f32_16x16x32_bf16 v[116:119], v[146:149], v[190:193], v[116:119]
	v_mfma_f32_16x16x32_bf16 v[112:115], v[154:157], v[190:193], v[112:115]
	v_mfma_f32_16x16x32_bf16 v[116:119], v[150:153], v[194:197], v[116:119]
	v_mfma_f32_16x16x32_bf16 v[112:115], v[158:161], v[194:197], v[112:115]
	v_mfma_f32_16x16x32_bf16 v[92:95], v[166:169], v[190:193], v[92:95]
	v_mfma_f32_16x16x32_bf16 v[88:91], v[174:177], v[190:193], v[88:91]
	v_mfma_f32_16x16x32_bf16 v[92:95], v[170:173], v[194:197], v[92:95]
	v_mfma_f32_16x16x32_bf16 v[88:91], v[178:181], v[194:197], v[88:91]
	s_cmp_eq_u32 s12, 0
	s_cbranch_scc1 .Lp10_skA2
	v_mfma_f32_16x16x32_bf16 v[100:103], v[146:149], v[198:201], v[100:103]
	v_mfma_f32_16x16x32_bf16 v[96:99], v[154:157], v[198:201], v[96:99]
	v_mfma_f32_16x16x32_bf16 v[100:103], v[150:153], v[202:205], v[100:103]
	v_mfma_f32_16x16x32_bf16 v[96:99], v[158:161], v[202:205], v[96:99]
	v_mfma_f32_16x16x32_bf16 v[76:79], v[166:169], v[198:201], v[76:79]
	v_mfma_f32_16x16x32_bf16 v[72:75], v[174:177], v[198:201], v[72:75]
	v_mfma_f32_16x16x32_bf16 v[76:79], v[170:173], v[202:205], v[76:79]
	v_mfma_f32_16x16x32_bf16 v[72:75], v[178:181], v[202:205], v[72:75]
.Lp10_skA2:
	s_barrier
	s_add_i32 s46, s71, s48
	v_lshl_add_u64 v[162:163], v[162:163], 0, s[10:11]
	s_mov_b32 m0, s46
	ds_read_b128 v[182:185], v145 offset:49152
	ds_read_b128 v[186:189], v145 offset:50176
	ds_read_b128 v[190:193], v145 offset:51200
	ds_read_b128 v[194:197], v145 offset:52224
	ds_read_b128 v[198:201], v145 offset:53248
	ds_read_b128 v[202:205], v145 offset:54272
	global_load_lds_dwordx4 v[162:163], off
	s_add_i32 m0, s46, 0x2000
	s_add_u32 s44, s44, 0xb0080
	v_lshl_add_u64 v[162:163], v[214:215], 0, s[10:11]
	s_addc_u32 s45, s45, 0
	s_add_i32 s46, s72, s48
	global_load_lds_dwordx4 v[162:163], off
	v_lshl_add_u64 v[162:163], s[44:45], 0, v[128:129]
	s_mov_b32 m0, s46
	s_nop 0
	global_load_lds_dwordx4 v[162:163], off
	v_lshl_add_u64 v[162:163], s[44:45], 0, v[130:131]
	s_add_i32 m0, s46, 0x2000
	s_nop 0
	global_load_lds_dwordx4 v[162:163], off
	v_lshl_add_u64 v[162:163], v[216:217], 0, s[10:11]
	s_nop 0
	v_lshl_add_u64 v[162:163], v[218:219], 0, s[10:11]
	s_mov_b32 m0, s57
	s_nop 0
	global_load_lds_dwordx4 v[162:163], off
	s_waitcnt vmcnt(6)
	s_waitcnt lgkmcnt(0)
	s_barrier
	s_waitcnt lgkmcnt(0)
	v_mfma_f32_16x16x32_bf16 v[60:63], v[146:149], v[182:185], v[60:63]
	v_mfma_f32_16x16x32_bf16 v[56:59], v[154:157], v[182:185], v[56:59]
	v_mfma_f32_16x16x32_bf16 v[60:63], v[150:153], v[186:189], v[60:63]
	v_mfma_f32_16x16x32_bf16 v[56:59], v[158:161], v[186:189], v[56:59]
	v_mfma_f32_16x16x32_bf16 v[44:47], v[166:169], v[182:185], v[44:47]
	v_mfma_f32_16x16x32_bf16 v[40:43], v[174:177], v[182:185], v[40:43]
	v_mfma_f32_16x16x32_bf16 v[44:47], v[170:173], v[186:189], v[44:47]
	v_mfma_f32_16x16x32_bf16 v[40:43], v[178:181], v[186:189], v[40:43]
	v_mfma_f32_16x16x32_bf16 v[52:55], v[146:149], v[190:193], v[52:55]
	v_mfma_f32_16x16x32_bf16 v[48:51], v[154:157], v[190:193], v[48:51]
	v_mfma_f32_16x16x32_bf16 v[52:55], v[150:153], v[194:197], v[52:55]
	v_mfma_f32_16x16x32_bf16 v[48:51], v[158:161], v[194:197], v[48:51]
	v_mfma_f32_16x16x32_bf16 v[28:31], v[166:169], v[190:193], v[28:31]
	v_mfma_f32_16x16x32_bf16 v[24:27], v[174:177], v[190:193], v[24:27]
	v_mfma_f32_16x16x32_bf16 v[28:31], v[170:173], v[194:197], v[28:31]
	v_mfma_f32_16x16x32_bf16 v[24:27], v[178:181], v[194:197], v[24:27]
	s_cmp_eq_u32 s12, 0
	s_cbranch_scc1 .Lp10_skA3
	v_mfma_f32_16x16x32_bf16 v[36:39], v[146:149], v[198:201], v[36:39]
	v_mfma_f32_16x16x32_bf16 v[32:35], v[154:157], v[198:201], v[32:35]
	v_mfma_f32_16x16x32_bf16 v[36:39], v[150:153], v[202:205], v[36:39]
	v_mfma_f32_16x16x32_bf16 v[32:35], v[158:161], v[202:205], v[32:35]
	v_mfma_f32_16x16x32_bf16 v[12:15], v[166:169], v[198:201], v[12:15]
	v_mfma_f32_16x16x32_bf16 v[8:11], v[174:177], v[198:201], v[8:11]
	v_mfma_f32_16x16x32_bf16 v[12:15], v[170:173], v[202:205], v[12:15]
	v_mfma_f32_16x16x32_bf16 v[8:11], v[178:181], v[202:205], v[8:11]
.Lp10_skA3:
	s_barrier
	s_add_i32 s70, s70, 2
	s_add_u32 s36, s36, 0x100
	s_addc_u32 s37, s37, 0
	s_add_u32 s68, s68, 0x100
	s_addc_u32 s69, s69, 0
	s_cmp_gt_u32 s70, 41
	s_cbranch_scc0 .Lp10_loopA
